# in-proj GEMM epilogue full-line stores issued with the nt (streaming) hint
# speedup vs baseline: 1.0178x; 1.0178x over previous
; #define PG8_STAGE(bufoff, gbase, voff) do { _Pragma("unroll") for (int _i = 0; _i < 2; ++_i) \
;         __builtin_amdgcn_global_load_lds((const unsigned*)((const char*)(gbase) + (voff)[_i]), (LAS unsigned*)(lds + (bufoff) + ldsw + _i * 8192), 16, 0, 0); } while (0)
; #define PG8_LDA(dst, b, h) do { _Pragma("unroll") for (int m = 0; m < 4; ++m) _Pragma("unroll") for (int k = 0; k < 2; ++k) dst[m][k] = *(const LAS bf16x8*)(lds + PG8_SA(b, h) + aoff + m * 2048 + k * 1024); } while (0)
; #define PG8_LDB(dst, b, h) do { _Pragma("unroll") for (int n = 0; n < 2; ++n) _Pragma("unroll") for (int k = 0; k < 2; ++k) dst[n][k] = *(const LAS bf16x8*)(lds + PG8_SB(b, h) + boff + n * 2048 + k * 1024); } while (0)
; #define PG8_MMA(ai, bj, At, Bt) do { __builtin_amdgcn_s_setprio(1); _Pragma("unroll") for (int m = 0; m < 4; ++m) _Pragma("unroll") for (int n = 0; n < 2; ++n) _Pragma("unroll") for (int k = 0; k < 2; ++k) \
;         acc[ai][bj][m][n] = __builtin_amdgcn_mfma_f32_16x16x32_bf16(Bt[n][k], At[m][k], acc[ai][bj][m][n], 0, 0, 0); __builtin_amdgcn_s_setprio(0); } while (0)
; #define PG8_WAIT_V(n) asm volatile("s_waitcnt vmcnt(" #n ")" ::: "memory")
; #define PG8_WAIT_L(n) asm volatile("s_waitcnt lgkmcnt(" #n ")" ::: "memory")
; #define PG8_BAR __builtin_amdgcn_s_barrier()
; #define PG8_SCHED __builtin_amdgcn_sched_barrier(0)
; template <class Epi, class Sched>
; DI void gemm_phase(LAS unsigned char* lds, const Gemm g, const Sched& S, const Epi& E) {
;     ...
;             PG8_LDB(B0, 0, 0); PG8_SCHED; PG8_LDA(At, 0, 0); PG8_STAGE(PG8_SA(1, 1), a1 + hstep, voffA);
;             PG8_WAIT_L(8); PG8_BAR; PG8_WAIT_L(0); PG8_MMA(0, 0, At, B0); PG8_BAR; PG8_SCHED;
;             PG8_LDB(B1, 0, 1); PG8_STAGE(PG8_SB(0, 0), b2, voffB);
;             PG8_BAR; PG8_WAIT_L(0); PG8_MMA(0, 1, At, B1); PG8_BAR;
;             PG8_LDA(At, 0, 1); PG8_STAGE(PG8_SA(0, 0), a2, voffA);
;             PG8_BAR; PG8_WAIT_L(0); PG8_MMA(1, 0, At, B0); PG8_BAR; PG8_SCHED;
;             PG8_STAGE(PG8_SB(0, 1), b2 + hstep, voffB);
;             PG8_WAIT_V(6); PG8_BAR; PG8_MMA(1, 1, At, B1); PG8_BAR;
.LBB0_130:
	ds_read_b128 v[156:159], v149
	ds_read_b128 v[160:163], v149 offset:1024
	ds_read_b128 v[164:167], v149 offset:2048
	ds_read_b128 v[168:171], v149 offset:3072
	s_add_u32 s26, s24, 0xfffc0080
	s_addc_u32 s27, s25, -1
	s_cmp_eq_u32 s45, 12
	s_cselect_b32 s29, s19, s27
	s_cselect_b32 s28, s41, s26
	s_cselect_b32 s27, s11, s44
	s_cselect_b32 s26, s42, s43
	v_lshl_add_u64 v[204:205], s[24:25], 0, v[138:139]
	s_add_i32 m0, s9, 0xc000
	ds_read_b128 v[172:175], v150
	ds_read_b128 v[176:179], v150 offset:1024
	ds_read_b128 v[180:183], v150 offset:2048
	ds_read_b128 v[184:187], v150 offset:3072
	ds_read_b128 v[188:191], v150 offset:4096
	ds_read_b128 v[192:195], v150 offset:5120
	ds_read_b128 v[196:199], v150 offset:6144
	ds_read_b128 v[200:203], v150 offset:7168
	global_load_lds_dwordx4 v[204:205], off
	v_lshl_add_u64 v[204:205], s[24:25], 0, v[140:141]
	s_add_i32 m0, s9, 0xe000
	s_nop 0
	global_load_lds_dwordx4 v[204:205], off
	s_waitcnt lgkmcnt(8)
	s_barrier
	s_waitcnt lgkmcnt(0)
	s_setprio 1
	s_waitcnt lgkmcnt(0)
	v_mfma_f32_16x16x32_bf16 v[126:129], v[156:159], v[172:175], v[126:129]
	v_mfma_f32_16x16x32_bf16 v[122:125], v[164:167], v[172:175], v[122:125]
	v_mfma_f32_16x16x32_bf16 v[118:121], v[156:159], v[180:183], v[118:121]
	v_mfma_f32_16x16x32_bf16 v[114:117], v[164:167], v[180:183], v[114:117]
	v_mfma_f32_16x16x32_bf16 v[102:105], v[156:159], v[188:191], v[102:105]
	v_mfma_f32_16x16x32_bf16 v[98:101], v[164:167], v[188:191], v[98:101]
	v_mfma_f32_16x16x32_bf16 v[86:89], v[156:159], v[196:199], v[86:89]
	v_mfma_f32_16x16x32_bf16 v[82:85], v[164:167], v[196:199], v[82:85]
	v_mfma_f32_16x16x32_bf16 v[126:129], v[160:163], v[176:179], v[126:129]
	v_mfma_f32_16x16x32_bf16 v[122:125], v[168:171], v[176:179], v[122:125]
	v_mfma_f32_16x16x32_bf16 v[118:121], v[160:163], v[184:187], v[118:121]
	v_mfma_f32_16x16x32_bf16 v[114:117], v[168:171], v[184:187], v[114:117]
	v_mfma_f32_16x16x32_bf16 v[102:105], v[160:163], v[192:195], v[102:105]
	v_mfma_f32_16x16x32_bf16 v[98:101], v[168:171], v[192:195], v[98:101]
	v_mfma_f32_16x16x32_bf16 v[86:89], v[160:163], v[200:203], v[86:89]
	v_mfma_f32_16x16x32_bf16 v[82:85], v[168:171], v[200:203], v[82:85]
	s_setprio 0
	s_barrier
	s_add_i32 s46, s37, s13
	v_lshl_add_u64 v[220:221], s[26:27], 0, v[134:135]
	s_mov_b32 m0, s46
	ds_read_b128 v[204:207], v151
	ds_read_b128 v[208:211], v151 offset:1024
	ds_read_b128 v[212:215], v151 offset:2048
	ds_read_b128 v[216:219], v151 offset:3072
	global_load_lds_dwordx4 v[220:221], off
	v_lshl_add_u64 v[222:223], s[26:27], 0, v[130:131]
	s_add_i32 m0, s46, 0x2000
	s_nop 0
	global_load_lds_dwordx4 v[222:223], off
	s_barrier
	s_waitcnt lgkmcnt(0)
	s_setprio 1
	s_waitcnt lgkmcnt(0)
	v_mfma_f32_16x16x32_bf16 v[110:113], v[204:207], v[172:175], v[110:113]
	v_mfma_f32_16x16x32_bf16 v[106:109], v[212:215], v[172:175], v[106:109]
	v_mfma_f32_16x16x32_bf16 v[94:97], v[204:207], v[180:183], v[94:97]
	v_mfma_f32_16x16x32_bf16 v[90:93], v[212:215], v[180:183], v[90:93]
	v_mfma_f32_16x16x32_bf16 v[78:81], v[204:207], v[188:191], v[78:81]
	v_mfma_f32_16x16x32_bf16 v[74:77], v[212:215], v[188:191], v[74:77]
	v_mfma_f32_16x16x32_bf16 v[70:73], v[204:207], v[196:199], v[70:73]
	v_mfma_f32_16x16x32_bf16 v[66:69], v[212:215], v[196:199], v[66:69]
	v_mfma_f32_16x16x32_bf16 v[110:113], v[208:211], v[176:179], v[110:113]
	v_mfma_f32_16x16x32_bf16 v[106:109], v[216:219], v[176:179], v[106:109]
	v_mfma_f32_16x16x32_bf16 v[94:97], v[208:211], v[184:187], v[94:97]
	v_mfma_f32_16x16x32_bf16 v[90:93], v[216:219], v[184:187], v[90:93]
	v_mfma_f32_16x16x32_bf16 v[78:81], v[208:211], v[192:195], v[78:81]
	v_mfma_f32_16x16x32_bf16 v[74:77], v[216:219], v[192:195], v[74:77]
	v_mfma_f32_16x16x32_bf16 v[70:73], v[208:211], v[200:203], v[70:73]
	v_mfma_f32_16x16x32_bf16 v[66:69], v[216:219], v[200:203], v[66:69]
	s_setprio 0
	s_mov_b32 m0, s9
	v_lshl_add_u64 v[224:225], s[28:29], 0, v[136:137]
	s_barrier
	ds_read_b128 v[172:175], v150 offset:16384
	ds_read_b128 v[176:179], v150 offset:17408
	ds_read_b128 v[180:183], v150 offset:18432
	ds_read_b128 v[184:187], v150 offset:19456
	ds_read_b128 v[188:191], v150 offset:20480
	ds_read_b128 v[192:195], v150 offset:21504
	ds_read_b128 v[196:199], v150 offset:22528
	ds_read_b128 v[200:203], v150 offset:23552
	global_load_lds_dwordx4 v[224:225], off
	v_lshl_add_u64 v[226:227], s[28:29], 0, v[132:133]
	s_mov_b32 m0, s30
	s_nop 0
	global_load_lds_dwordx4 v[226:227], off
	s_barrier
	s_waitcnt lgkmcnt(0)
	s_setprio 1
	s_waitcnt lgkmcnt(0)
	v_mfma_f32_16x16x32_bf16 v[62:65], v[156:159], v[172:175], v[62:65]
	v_mfma_f32_16x16x32_bf16 v[58:61], v[164:167], v[172:175], v[58:61]
	v_mfma_f32_16x16x32_bf16 v[54:57], v[156:159], v[180:183], v[54:57]
	v_mfma_f32_16x16x32_bf16 v[50:53], v[164:167], v[180:183], v[50:53]
	v_mfma_f32_16x16x32_bf16 v[38:41], v[156:159], v[188:191], v[38:41]
	v_mfma_f32_16x16x32_bf16 v[34:37], v[164:167], v[188:191], v[34:37]
	v_mfma_f32_16x16x32_bf16 v[22:25], v[156:159], v[196:199], v[22:25]
	v_mfma_f32_16x16x32_bf16 v[18:21], v[164:167], v[196:199], v[18:21]
	v_mfma_f32_16x16x32_bf16 v[62:65], v[160:163], v[176:179], v[62:65]
	v_mfma_f32_16x16x32_bf16 v[58:61], v[168:171], v[176:179], v[58:61]
	v_mfma_f32_16x16x32_bf16 v[54:57], v[160:163], v[184:187], v[54:57]
	v_mfma_f32_16x16x32_bf16 v[50:53], v[168:171], v[184:187], v[50:53]
	v_mfma_f32_16x16x32_bf16 v[38:41], v[160:163], v[192:195], v[38:41]
	v_mfma_f32_16x16x32_bf16 v[34:37], v[168:171], v[192:195], v[34:37]
	v_mfma_f32_16x16x32_bf16 v[22:25], v[160:163], v[200:203], v[22:25]
	v_mfma_f32_16x16x32_bf16 v[18:21], v[168:171], v[200:203], v[18:21]
	s_setprio 0
	s_barrier
; #define PG8_STAGE(bufoff, gbase, voff) do { _Pragma("unroll") for (int _i = 0; _i < 2; ++_i) \
;         __builtin_amdgcn_global_load_lds((const unsigned*)((const char*)(gbase) + (voff)[_i]), (LAS unsigned*)(lds + (bufoff) + ldsw + _i * 8192), 16, 0, 0); } while (0)
; #define PG8_LDA(dst, b, h) do { _Pragma("unroll") for (int m = 0; m < 4; ++m) _Pragma("unroll") for (int k = 0; k < 2; ++k) dst[m][k] = *(const LAS bf16x8*)(lds + PG8_SA(b, h) + aoff + m * 2048 + k * 1024); } while (0)
; #define PG8_LDB(dst, b, h) do { _Pragma("unroll") for (int n = 0; n < 2; ++n) _Pragma("unroll") for (int k = 0; k < 2; ++k) dst[n][k] = *(const LAS bf16x8*)(lds + PG8_SB(b, h) + boff + n * 2048 + k * 1024); } while (0)
; #define PG8_MMA(ai, bj, At, Bt) do { __builtin_amdgcn_s_setprio(1); _Pragma("unroll") for (int m = 0; m < 4; ++m) _Pragma("unroll") for (int n = 0; n < 2; ++n) _Pragma("unroll") for (int k = 0; k < 2; ++k) \
;         acc[ai][bj][m][n] = __builtin_amdgcn_mfma_f32_16x16x32_bf16(Bt[n][k], At[m][k], acc[ai][bj][m][n], 0, 0, 0); __builtin_amdgcn_s_setprio(0); } while (0)
; #define PG8_WAIT_V(n) asm volatile("s_waitcnt vmcnt(" #n ")" ::: "memory")
; #define PG8_WAIT_L(n) asm volatile("s_waitcnt lgkmcnt(" #n ")" ::: "memory")
; #define PG8_BAR __builtin_amdgcn_s_barrier()
; #define PG8_SCHED __builtin_amdgcn_sched_barrier(0)
; template <class Epi, class Sched>
; DI void gemm_phase(LAS unsigned char* lds, const Gemm g, const Sched& S, const Epi& E) {
;     ...
;             PG8_STAGE(PG8_SB(0, 1), b2 + hstep, voffB);
;             PG8_WAIT_V(6); PG8_BAR; PG8_MMA(1, 1, At, B1); PG8_BAR;
;             PG8_LDB(B0, 1, 0); PG8_SCHED; PG8_LDA(At, 1, 0); PG8_STAGE(PG8_SA(0, 1), a2 + hstep, voffA);
;             PG8_WAIT_L(8); PG8_BAR; PG8_WAIT_L(0); PG8_MMA(0, 0, At, B0); PG8_BAR; PG8_SCHED;
;             PG8_LDB(B1, 1, 1); PG8_STAGE(PG8_SB(1, 0), b3, voffB);
;             PG8_BAR; PG8_WAIT_L(0); PG8_MMA(0, 1, At, B1); PG8_BAR;
;             PG8_LDA(At, 1, 1); PG8_STAGE(PG8_SA(1, 0), a3, voffA);
;             PG8_BAR; PG8_WAIT_L(0); PG8_MMA(1, 0, At, B0); PG8_BAR; PG8_SCHED;
	s_add_u32 s46, s26, 0x10000
	s_addc_u32 s47, s27, 0
	s_add_i32 s48, s38, s13
	v_lshl_add_u64 v[156:157], s[46:47], 0, v[134:135]
	s_mov_b32 m0, s48
	s_nop 0
	global_load_lds_dwordx4 v[156:157], off
	v_lshl_add_u64 v[156:157], s[46:47], 0, v[130:131]
	s_add_i32 m0, s48, 0x2000
	s_nop 0
	global_load_lds_dwordx4 v[156:157], off
	s_waitcnt vmcnt(6)
	s_barrier
	s_setprio 1
	v_mfma_f32_16x16x32_bf16 v[46:49], v[204:207], v[172:175], v[46:49]
	v_mfma_f32_16x16x32_bf16 v[42:45], v[212:215], v[172:175], v[42:45]
	v_mfma_f32_16x16x32_bf16 v[30:33], v[204:207], v[180:183], v[30:33]
	v_mfma_f32_16x16x32_bf16 v[26:29], v[212:215], v[180:183], v[26:29]
	v_mfma_f32_16x16x32_bf16 v[14:17], v[204:207], v[188:191], v[14:17]
	v_mfma_f32_16x16x32_bf16 v[10:13], v[212:215], v[188:191], v[10:13]
	v_mfma_f32_16x16x32_bf16 v[6:9], v[204:207], v[196:199], v[6:9]
	v_mfma_f32_16x16x32_bf16 v[2:5], v[212:215], v[196:199], v[2:5]
	v_mfma_f32_16x16x32_bf16 v[46:49], v[208:211], v[176:179], v[46:49]
	v_mfma_f32_16x16x32_bf16 v[42:45], v[216:219], v[176:179], v[42:45]
	v_mfma_f32_16x16x32_bf16 v[30:33], v[208:211], v[184:187], v[30:33]
	v_mfma_f32_16x16x32_bf16 v[26:29], v[216:219], v[184:187], v[26:29]
	v_mfma_f32_16x16x32_bf16 v[14:17], v[208:211], v[192:195], v[14:17]
	v_mfma_f32_16x16x32_bf16 v[10:13], v[216:219], v[192:195], v[10:13]
	v_mfma_f32_16x16x32_bf16 v[6:9], v[208:211], v[200:203], v[6:9]
	v_mfma_f32_16x16x32_bf16 v[2:5], v[216:219], v[200:203], v[2:5]
	s_setprio 0
	s_add_i32 s46, 0, 0x18000
	v_add_u32_e32 v154, s46, v147
	s_barrier
	ds_read_b128 v[156:159], v154
	ds_read_b128 v[160:163], v154 offset:1024
	ds_read_b128 v[164:167], v154 offset:2048
	ds_read_b128 v[168:171], v154 offset:3072
	s_add_u32 s28, s28, 0x40000
	s_addc_u32 s29, s29, 0
	s_mov_b32 m0, s31
	v_lshl_add_u64 v[204:205], s[28:29], 0, v[136:137]
	ds_read_b128 v[172:175], v150 offset:32768
	ds_read_b128 v[176:179], v150 offset:33792
	ds_read_b128 v[180:183], v150 offset:34816
	ds_read_b128 v[184:187], v150 offset:35840
	ds_read_b128 v[188:191], v150 offset:36864
	ds_read_b128 v[192:195], v150 offset:37888
	ds_read_b128 v[196:199], v150 offset:38912
	ds_read_b128 v[200:203], v150 offset:39936
	global_load_lds_dwordx4 v[204:205], off
	v_lshl_add_u64 v[204:205], s[28:29], 0, v[132:133]
	s_mov_b32 m0, s33
	s_nop 0
	global_load_lds_dwordx4 v[204:205], off
	s_waitcnt lgkmcnt(8)
	s_barrier
	s_waitcnt lgkmcnt(0)
	s_setprio 1
	s_waitcnt lgkmcnt(0)
	v_mfma_f32_16x16x32_bf16 v[126:129], v[156:159], v[172:175], v[126:129]
	v_mfma_f32_16x16x32_bf16 v[122:125], v[164:167], v[172:175], v[122:125]
	v_mfma_f32_16x16x32_bf16 v[118:121], v[156:159], v[180:183], v[118:121]
	v_mfma_f32_16x16x32_bf16 v[114:117], v[164:167], v[180:183], v[114:117]
	v_mfma_f32_16x16x32_bf16 v[102:105], v[156:159], v[188:191], v[102:105]
	v_mfma_f32_16x16x32_bf16 v[98:101], v[164:167], v[188:191], v[98:101]
	v_mfma_f32_16x16x32_bf16 v[86:89], v[156:159], v[196:199], v[86:89]
	v_mfma_f32_16x16x32_bf16 v[82:85], v[164:167], v[196:199], v[82:85]
	v_mfma_f32_16x16x32_bf16 v[126:129], v[160:163], v[176:179], v[126:129]
	v_mfma_f32_16x16x32_bf16 v[122:125], v[168:171], v[176:179], v[122:125]
	v_mfma_f32_16x16x32_bf16 v[118:121], v[160:163], v[184:187], v[118:121]
	v_mfma_f32_16x16x32_bf16 v[114:117], v[168:171], v[184:187], v[114:117]
	v_mfma_f32_16x16x32_bf16 v[102:105], v[160:163], v[192:195], v[102:105]
	v_mfma_f32_16x16x32_bf16 v[98:101], v[168:171], v[192:195], v[98:101]
	v_mfma_f32_16x16x32_bf16 v[86:89], v[160:163], v[200:203], v[86:89]
	v_mfma_f32_16x16x32_bf16 v[82:85], v[168:171], v[200:203], v[82:85]
	s_setprio 0
	s_barrier
	s_add_i32 s28, 0, 0x1c000
	s_add_i32 s29, s46, s13
	v_add_u32_e32 v154, s28, v147
	v_lshl_add_u64 v[220:221], v[220:221], 0, s[6:7]
	s_mov_b32 m0, s29
	ds_read_b128 v[204:207], v154
	ds_read_b128 v[208:211], v154 offset:1024
	ds_read_b128 v[212:215], v154 offset:2048
	ds_read_b128 v[216:219], v154 offset:3072
	global_load_lds_dwordx4 v[220:221], off
	v_lshl_add_u64 v[220:221], v[222:223], 0, s[6:7]
	s_add_i32 m0, s29, 0x2000
	s_nop 0
	global_load_lds_dwordx4 v[220:221], off
	s_barrier
	s_waitcnt lgkmcnt(0)
	s_setprio 1
	s_waitcnt lgkmcnt(0)
	v_mfma_f32_16x16x32_bf16 v[110:113], v[204:207], v[172:175], v[110:113]
	v_mfma_f32_16x16x32_bf16 v[106:109], v[212:215], v[172:175], v[106:109]
	v_mfma_f32_16x16x32_bf16 v[94:97], v[204:207], v[180:183], v[94:97]
	v_mfma_f32_16x16x32_bf16 v[90:93], v[212:215], v[180:183], v[90:93]
	v_mfma_f32_16x16x32_bf16 v[78:81], v[204:207], v[188:191], v[78:81]
	v_mfma_f32_16x16x32_bf16 v[74:77], v[212:215], v[188:191], v[74:77]
	v_mfma_f32_16x16x32_bf16 v[70:73], v[204:207], v[196:199], v[70:73]
	v_mfma_f32_16x16x32_bf16 v[66:69], v[212:215], v[196:199], v[66:69]
	v_mfma_f32_16x16x32_bf16 v[110:113], v[208:211], v[176:179], v[110:113]
	v_mfma_f32_16x16x32_bf16 v[106:109], v[216:219], v[176:179], v[106:109]
	v_mfma_f32_16x16x32_bf16 v[94:97], v[208:211], v[184:187], v[94:97]
	v_mfma_f32_16x16x32_bf16 v[90:93], v[216:219], v[184:187], v[90:93]
	v_mfma_f32_16x16x32_bf16 v[78:81], v[208:211], v[192:195], v[78:81]
	v_mfma_f32_16x16x32_bf16 v[74:77], v[216:219], v[192:195], v[74:77]
	v_mfma_f32_16x16x32_bf16 v[70:73], v[208:211], v[200:203], v[70:73]
	v_mfma_f32_16x16x32_bf16 v[66:69], v[216:219], v[200:203], v[66:69]
	s_setprio 0
	s_mov_b32 m0, s35
	v_lshl_add_u64 v[220:221], v[224:225], 0, s[6:7]
	s_barrier
	ds_read_b128 v[172:175], v150 offset:49152
	ds_read_b128 v[176:179], v150 offset:50176
	ds_read_b128 v[180:183], v150 offset:51200
	ds_read_b128 v[184:187], v150 offset:52224
	ds_read_b128 v[188:191], v150 offset:53248
	ds_read_b128 v[192:195], v150 offset:54272
	ds_read_b128 v[196:199], v150 offset:55296
	ds_read_b128 v[200:203], v150 offset:56320
	global_load_lds_dwordx4 v[220:221], off
	v_lshl_add_u64 v[220:221], v[226:227], 0, s[6:7]
	s_mov_b32 m0, s36
	s_nop 0
	global_load_lds_dwordx4 v[220:221], off
	s_barrier
; DI unsigned pk_bf16(float a, float b) { f32x2 v = {a, b}; bf2_t r = __builtin_convertvector(v, bf2_t); return __builtin_bit_cast(unsigned, r); }
; #define PG8_STAGE(bufoff, gbase, voff) do { _Pragma("unroll") for (int _i = 0; _i < 2; ++_i) \
;         __builtin_amdgcn_global_load_lds((const unsigned*)((const char*)(gbase) + (voff)[_i]), (LAS unsigned*)(lds + (bufoff) + ldsw + _i * 8192), 16, 0, 0); } while (0)
; #define PG8_LDA(dst, b, h) do { _Pragma("unroll") for (int m = 0; m < 4; ++m) _Pragma("unroll") for (int k = 0; k < 2; ++k) dst[m][k] = *(const LAS bf16x8*)(lds + PG8_SA(b, h) + aoff + m * 2048 + k * 1024); } while (0)
; #define PG8_LDB(dst, b, h) do { _Pragma("unroll") for (int n = 0; n < 2; ++n) _Pragma("unroll") for (int k = 0; k < 2; ++k) dst[n][k] = *(const LAS bf16x8*)(lds + PG8_SB(b, h) + boff + n * 2048 + k * 1024); } while (0)
; #define PG8_WAIT_V(n) asm volatile("s_waitcnt vmcnt(" #n ")" ::: "memory")
; #define PG8_BAR __builtin_amdgcn_s_barrier()
;     DI void operator()(const f32x4 (&acc)[2][2][4][2], const Unit& u, int wr, int wc, int fr, int fq) const {
;         const int row0 = u.pm * BM + wr * 64 + fr, col0 = u.pn * BM + wc * 32 + 8 * fq;
; #pragma unroll
;         for (int ai = 0; ai < 2; ++ai)
; #pragma unroll
;             for (int m = 0; m < 4; ++m) { bf16_t* rowp = O + (size_t)(row0 + ai * HALF + m * 16) * ldc + col0;
; #pragma unroll
;                 for (int bj = 0; bj < 2; ++bj) { const f32x4 v0 = acc[ai][bj][m][0], v1 = acc[ai][bj][m][1];
;                     u32x4 w; w.x = pk_bf16(v0[0], v0[1]); w.y = pk_bf16(v0[2], v0[3]); w.z = pk_bf16(v1[0], v1[1]); w.w = pk_bf16(v1[2], v1[3]);
;                     *(u32x4*)(rowp + bj * HALF) = w; } }
; template <class Epi, class Sched>
; DI void gemm_phase(LAS unsigned char* lds, const Gemm g, const Sched& S, const Epi& E) {
;     ...
;             PG8_WAIT_L(8); PG8_BAR; PG8_WAIT_L(0); PG8_MMA(0, 0, At, B0); PG8_BAR; PG8_SCHED;
;             PG8_LDB(B1, 1, 1); PG8_STAGE(PG8_SB(1, 0), b3, voffB);
;             PG8_BAR; PG8_WAIT_L(0); PG8_MMA(0, 1, At, B1); PG8_BAR;
;             PG8_LDA(At, 1, 1); PG8_STAGE(PG8_SA(1, 0), a3, voffA);
;             PG8_BAR; PG8_WAIT_L(0); PG8_MMA(1, 0, At, B0); PG8_BAR; PG8_SCHED;
;             PG8_STAGE(PG8_SB(1, 1), b3 + hstep, voffB);
;             PG8_WAIT_V(6); PG8_BAR; PG8_MMA(1, 1, At, B1); PG8_BAR;
;         }
;         E(acc, cur, wr, wc, fr, fq);
	s_waitcnt lgkmcnt(0)
	s_setprio 1
	s_waitcnt lgkmcnt(0)
	v_mfma_f32_16x16x32_bf16 v[62:65], v[156:159], v[172:175], v[62:65]
	v_mfma_f32_16x16x32_bf16 v[58:61], v[164:167], v[172:175], v[58:61]
	v_mfma_f32_16x16x32_bf16 v[54:57], v[156:159], v[180:183], v[54:57]
	v_mfma_f32_16x16x32_bf16 v[50:53], v[164:167], v[180:183], v[50:53]
	v_mfma_f32_16x16x32_bf16 v[38:41], v[156:159], v[188:191], v[38:41]
	v_mfma_f32_16x16x32_bf16 v[34:37], v[164:167], v[188:191], v[34:37]
	v_mfma_f32_16x16x32_bf16 v[22:25], v[156:159], v[196:199], v[22:25]
	v_mfma_f32_16x16x32_bf16 v[18:21], v[164:167], v[196:199], v[18:21]
	v_mfma_f32_16x16x32_bf16 v[62:65], v[160:163], v[176:179], v[62:65]
	v_mfma_f32_16x16x32_bf16 v[58:61], v[168:171], v[176:179], v[58:61]
	v_mfma_f32_16x16x32_bf16 v[54:57], v[160:163], v[184:187], v[54:57]
	v_mfma_f32_16x16x32_bf16 v[50:53], v[168:171], v[184:187], v[50:53]
	v_mfma_f32_16x16x32_bf16 v[38:41], v[160:163], v[192:195], v[38:41]
	v_mfma_f32_16x16x32_bf16 v[34:37], v[168:171], v[192:195], v[34:37]
	v_mfma_f32_16x16x32_bf16 v[22:25], v[160:163], v[200:203], v[22:25]
	v_mfma_f32_16x16x32_bf16 v[18:21], v[168:171], v[200:203], v[18:21]
	s_setprio 0
	s_barrier
	s_add_u32 s26, s26, 0x10080
	s_addc_u32 s27, s27, 0
	s_add_i32 s28, s28, s13
	v_lshl_add_u64 v[156:157], s[26:27], 0, v[134:135]
	s_mov_b32 m0, s28
	s_nop 0
	global_load_lds_dwordx4 v[156:157], off
	v_lshl_add_u64 v[156:157], s[26:27], 0, v[130:131]
	s_add_i32 m0, s28, 0x2000
	s_nop 0
	global_load_lds_dwordx4 v[156:157], off
	s_waitcnt vmcnt(6)
	s_barrier
	s_setprio 1
	v_mfma_f32_16x16x32_bf16 v[46:49], v[204:207], v[172:175], v[46:49]
	v_mfma_f32_16x16x32_bf16 v[42:45], v[212:215], v[172:175], v[42:45]
	v_mfma_f32_16x16x32_bf16 v[30:33], v[204:207], v[180:183], v[30:33]
	v_mfma_f32_16x16x32_bf16 v[26:29], v[212:215], v[180:183], v[26:29]
	v_mfma_f32_16x16x32_bf16 v[14:17], v[204:207], v[188:191], v[14:17]
	v_mfma_f32_16x16x32_bf16 v[10:13], v[212:215], v[188:191], v[10:13]
	v_mfma_f32_16x16x32_bf16 v[6:9], v[204:207], v[196:199], v[6:9]
	v_mfma_f32_16x16x32_bf16 v[2:5], v[212:215], v[196:199], v[2:5]
	v_mfma_f32_16x16x32_bf16 v[46:49], v[208:211], v[176:179], v[46:49]
	v_mfma_f32_16x16x32_bf16 v[42:45], v[216:219], v[176:179], v[42:45]
	v_mfma_f32_16x16x32_bf16 v[30:33], v[208:211], v[184:187], v[30:33]
	v_mfma_f32_16x16x32_bf16 v[26:29], v[216:219], v[184:187], v[26:29]
	v_mfma_f32_16x16x32_bf16 v[14:17], v[208:211], v[192:195], v[14:17]
	v_mfma_f32_16x16x32_bf16 v[10:13], v[216:219], v[192:195], v[10:13]
	v_mfma_f32_16x16x32_bf16 v[6:9], v[208:211], v[200:203], v[6:9]
	v_mfma_f32_16x16x32_bf16 v[2:5], v[216:219], v[200:203], v[2:5]
	s_setprio 0
	s_add_i32 s45, s45, 2
	s_add_u32 s24, s24, 0x100
	s_addc_u32 s25, s25, 0
	s_add_u32 s43, s43, 0x100
	s_addc_u32 s44, s44, 0
	s_cmp_gt_u32 s45, 13
	s_barrier
	s_cbranch_scc0 .LBB0_130
	v_and_b32_e32 v156, 8, v146
	v_sub_u32_e32 v157, v146, v156
	v_lshl_add_u32 v157, s8, 8, v157
	v_lshl_add_u32 v156, v156, 2, v148
	v_lshl_or_b32 v156, s40, 8, v156
	v_mul_u32_u24_e32 v157, 0x2200, v157
	v_lshl_add_u32 v244, v156, 1, v157
	v_add_u32_e32 v245, 0x11000, v244
	v_add_u32_e32 v246, 0x22000, v244
	v_add_u32_e32 v247, 0x33000, v244
	v_add_u32_e32 v248, 0x44000, v244
	v_add_u32_e32 v249, 0x55000, v244
	v_add_u32_e32 v250, 0x66000, v244
	v_add_u32_e32 v251, 0x77000, v244
	v_add_u32_e32 v252, 0x110000, v244
	v_add_u32_e32 v253, 0x121000, v244
	v_add_u32_e32 v254, 0x132000, v244
	v_add_u32_e32 v255, 0x143000, v244
	v_add_u32_e32 v158, 0x154000, v244
	v_add_u32_e32 v159, 0x165000, v244
	v_add_u32_e32 v160, 0x176000, v244
	v_add_u32_e32 v161, 0x187000, v244
	s_and_b64 vcc, exec, s[0:1]
	s_mov_b32 s40, s10
	s_mov_b32 s8, s18
	s_mov_b64 s[26:27], s[22:23]
	s_mov_b64 s[24:25], s[20:21]
	v_cvt_pk_bf16_f32 v126, v126, v127
	v_cvt_pk_bf16_f32 v127, v128, v129
	v_cvt_pk_bf16_f32 v128, v122, v123
	v_cvt_pk_bf16_f32 v129, v124, v125
	v_cvt_pk_bf16_f32 v110, v110, v111
	v_cvt_pk_bf16_f32 v111, v112, v113
	v_cvt_pk_bf16_f32 v112, v106, v107
	v_cvt_pk_bf16_f32 v113, v108, v109
	v_mov_b32_dpp v240, v126 row_ror:8 row_mask:0xf bank_mask:0xf
	v_mov_b32_dpp v241, v127 row_ror:8 row_mask:0xf bank_mask:0xf
	v_mov_b32_dpp v242, v128 row_ror:8 row_mask:0xf bank_mask:0xf
	v_mov_b32_dpp v243, v129 row_ror:8 row_mask:0xf bank_mask:0xf
	v_mov_b32_dpp v126, v110 row_ror:8 row_mask:0xf bank_mask:0xc
	v_mov_b32_dpp v127, v111 row_ror:8 row_mask:0xf bank_mask:0xc
	v_mov_b32_dpp v128, v112 row_ror:8 row_mask:0xf bank_mask:0xc
	v_mov_b32_dpp v129, v113 row_ror:8 row_mask:0xf bank_mask:0xc
	v_mov_b32_dpp v110, v240 quad_perm:[0,1,2,3] row_mask:0xf bank_mask:0x3
	v_mov_b32_dpp v111, v241 quad_perm:[0,1,2,3] row_mask:0xf bank_mask:0x3
	v_mov_b32_dpp v112, v242 quad_perm:[0,1,2,3] row_mask:0xf bank_mask:0x3
	v_mov_b32_dpp v113, v243 quad_perm:[0,1,2,3] row_mask:0xf bank_mask:0x3
	global_store_dwordx4 v244, v[126:129], s[86:87] nt
	global_store_dwordx4 v245, v[110:113], s[86:87] nt
	v_cvt_pk_bf16_f32 v118, v118, v119
	v_cvt_pk_bf16_f32 v119, v120, v121
	v_cvt_pk_bf16_f32 v120, v114, v115
	v_cvt_pk_bf16_f32 v121, v116, v117
	v_cvt_pk_bf16_f32 v94, v94, v95
	v_cvt_pk_bf16_f32 v95, v96, v97
	v_cvt_pk_bf16_f32 v96, v90, v91
	v_cvt_pk_bf16_f32 v97, v92, v93
	v_mov_b32_dpp v240, v118 row_ror:8 row_mask:0xf bank_mask:0xf
	v_mov_b32_dpp v241, v119 row_ror:8 row_mask:0xf bank_mask:0xf
	v_mov_b32_dpp v242, v120 row_ror:8 row_mask:0xf bank_mask:0xf
	v_mov_b32_dpp v243, v121 row_ror:8 row_mask:0xf bank_mask:0xf
	v_mov_b32_dpp v118, v94 row_ror:8 row_mask:0xf bank_mask:0xc
	v_mov_b32_dpp v119, v95 row_ror:8 row_mask:0xf bank_mask:0xc
	v_mov_b32_dpp v120, v96 row_ror:8 row_mask:0xf bank_mask:0xc
; DI unsigned pk_bf16(float a, float b) { f32x2 v = {a, b}; bf2_t r = __builtin_convertvector(v, bf2_t); return __builtin_bit_cast(unsigned, r); }
;     DI void operator()(const f32x4 (&acc)[2][2][4][2], const Unit& u, int wr, int wc, int fr, int fq) const {
;     ...
;             for (int m = 0; m < 4; ++m) { bf16_t* rowp = O + (size_t)(row0 + ai * HALF + m * 16) * ldc + col0;
; #pragma unroll
;                 for (int bj = 0; bj < 2; ++bj) { const f32x4 v0 = acc[ai][bj][m][0], v1 = acc[ai][bj][m][1];
;                     u32x4 w; w.x = pk_bf16(v0[0], v0[1]); w.y = pk_bf16(v0[2], v0[3]); w.z = pk_bf16(v1[0], v1[1]); w.w = pk_bf16(v1[2], v1[3]);
;                     *(u32x4*)(rowp + bj * HALF) = w; } }
	v_mov_b32_dpp v121, v97 row_ror:8 row_mask:0xf bank_mask:0xc
	v_mov_b32_dpp v94, v240 quad_perm:[0,1,2,3] row_mask:0xf bank_mask:0x3
	v_mov_b32_dpp v95, v241 quad_perm:[0,1,2,3] row_mask:0xf bank_mask:0x3
	v_mov_b32_dpp v96, v242 quad_perm:[0,1,2,3] row_mask:0xf bank_mask:0x3
	v_mov_b32_dpp v97, v243 quad_perm:[0,1,2,3] row_mask:0xf bank_mask:0x3
	global_store_dwordx4 v246, v[118:121], s[86:87] nt
	global_store_dwordx4 v247, v[94:97], s[86:87] nt
	v_cvt_pk_bf16_f32 v102, v102, v103
	v_cvt_pk_bf16_f32 v103, v104, v105
	v_cvt_pk_bf16_f32 v104, v98, v99
	v_cvt_pk_bf16_f32 v105, v100, v101
	v_cvt_pk_bf16_f32 v78, v78, v79
	v_cvt_pk_bf16_f32 v79, v80, v81
	v_cvt_pk_bf16_f32 v80, v74, v75
	v_cvt_pk_bf16_f32 v81, v76, v77
	v_mov_b32_dpp v240, v102 row_ror:8 row_mask:0xf bank_mask:0xf
	v_mov_b32_dpp v241, v103 row_ror:8 row_mask:0xf bank_mask:0xf
	v_mov_b32_dpp v242, v104 row_ror:8 row_mask:0xf bank_mask:0xf
	v_mov_b32_dpp v243, v105 row_ror:8 row_mask:0xf bank_mask:0xf
	v_mov_b32_dpp v102, v78 row_ror:8 row_mask:0xf bank_mask:0xc
	v_mov_b32_dpp v103, v79 row_ror:8 row_mask:0xf bank_mask:0xc
	v_mov_b32_dpp v104, v80 row_ror:8 row_mask:0xf bank_mask:0xc
	v_mov_b32_dpp v105, v81 row_ror:8 row_mask:0xf bank_mask:0xc
	v_mov_b32_dpp v78, v240 quad_perm:[0,1,2,3] row_mask:0xf bank_mask:0x3
	v_mov_b32_dpp v79, v241 quad_perm:[0,1,2,3] row_mask:0xf bank_mask:0x3
	v_mov_b32_dpp v80, v242 quad_perm:[0,1,2,3] row_mask:0xf bank_mask:0x3
	v_mov_b32_dpp v81, v243 quad_perm:[0,1,2,3] row_mask:0xf bank_mask:0x3
	global_store_dwordx4 v248, v[102:105], s[86:87] nt
	global_store_dwordx4 v249, v[78:81], s[86:87] nt
	v_cvt_pk_bf16_f32 v86, v86, v87
	v_cvt_pk_bf16_f32 v87, v88, v89
	v_cvt_pk_bf16_f32 v88, v82, v83
	v_cvt_pk_bf16_f32 v89, v84, v85
	v_cvt_pk_bf16_f32 v70, v70, v71
	v_cvt_pk_bf16_f32 v71, v72, v73
	v_cvt_pk_bf16_f32 v72, v66, v67
	v_cvt_pk_bf16_f32 v73, v68, v69
	v_mov_b32_dpp v240, v86 row_ror:8 row_mask:0xf bank_mask:0xf
	v_mov_b32_dpp v241, v87 row_ror:8 row_mask:0xf bank_mask:0xf
	v_mov_b32_dpp v242, v88 row_ror:8 row_mask:0xf bank_mask:0xf
	v_mov_b32_dpp v243, v89 row_ror:8 row_mask:0xf bank_mask:0xf
	v_mov_b32_dpp v86, v70 row_ror:8 row_mask:0xf bank_mask:0xc
	v_mov_b32_dpp v87, v71 row_ror:8 row_mask:0xf bank_mask:0xc
	v_mov_b32_dpp v88, v72 row_ror:8 row_mask:0xf bank_mask:0xc
	v_mov_b32_dpp v89, v73 row_ror:8 row_mask:0xf bank_mask:0xc
	v_mov_b32_dpp v70, v240 quad_perm:[0,1,2,3] row_mask:0xf bank_mask:0x3
	v_mov_b32_dpp v71, v241 quad_perm:[0,1,2,3] row_mask:0xf bank_mask:0x3
	v_mov_b32_dpp v72, v242 quad_perm:[0,1,2,3] row_mask:0xf bank_mask:0x3
	v_mov_b32_dpp v73, v243 quad_perm:[0,1,2,3] row_mask:0xf bank_mask:0x3
	global_store_dwordx4 v250, v[86:89], s[86:87] nt
	global_store_dwordx4 v251, v[70:73], s[86:87] nt
	v_cvt_pk_bf16_f32 v62, v62, v63
	v_cvt_pk_bf16_f32 v63, v64, v65
	v_cvt_pk_bf16_f32 v64, v58, v59
	v_cvt_pk_bf16_f32 v65, v60, v61
	v_cvt_pk_bf16_f32 v46, v46, v47
	v_cvt_pk_bf16_f32 v47, v48, v49
	v_cvt_pk_bf16_f32 v48, v42, v43
	v_cvt_pk_bf16_f32 v49, v44, v45
	v_mov_b32_dpp v240, v62 row_ror:8 row_mask:0xf bank_mask:0xf
	v_mov_b32_dpp v241, v63 row_ror:8 row_mask:0xf bank_mask:0xf
	v_mov_b32_dpp v242, v64 row_ror:8 row_mask:0xf bank_mask:0xf
	v_mov_b32_dpp v243, v65 row_ror:8 row_mask:0xf bank_mask:0xf
	v_mov_b32_dpp v62, v46 row_ror:8 row_mask:0xf bank_mask:0xc
	v_mov_b32_dpp v63, v47 row_ror:8 row_mask:0xf bank_mask:0xc
	v_mov_b32_dpp v64, v48 row_ror:8 row_mask:0xf bank_mask:0xc
	v_mov_b32_dpp v65, v49 row_ror:8 row_mask:0xf bank_mask:0xc
	v_mov_b32_dpp v46, v240 quad_perm:[0,1,2,3] row_mask:0xf bank_mask:0x3
	v_mov_b32_dpp v47, v241 quad_perm:[0,1,2,3] row_mask:0xf bank_mask:0x3
	v_mov_b32_dpp v48, v242 quad_perm:[0,1,2,3] row_mask:0xf bank_mask:0x3
; DI unsigned pk_bf16(float a, float b) { f32x2 v = {a, b}; bf2_t r = __builtin_convertvector(v, bf2_t); return __builtin_bit_cast(unsigned, r); }
; #define PG8_WAIT_V(n) asm volatile("s_waitcnt vmcnt(" #n ")" ::: "memory")
; #define PG8_BAR __builtin_amdgcn_s_barrier()
;     DI void operator()(const f32x4 (&acc)[2][2][4][2], const Unit& u, int wr, int wc, int fr, int fq) const {
;     ...
;             for (int m = 0; m < 4; ++m) { bf16_t* rowp = O + (size_t)(row0 + ai * HALF + m * 16) * ldc + col0;
; #pragma unroll
;                 for (int bj = 0; bj < 2; ++bj) { const f32x4 v0 = acc[ai][bj][m][0], v1 = acc[ai][bj][m][1];
;                     u32x4 w; w.x = pk_bf16(v0[0], v0[1]); w.y = pk_bf16(v0[2], v0[3]); w.z = pk_bf16(v1[0], v1[1]); w.w = pk_bf16(v1[2], v1[3]);
;                     *(u32x4*)(rowp + bj * HALF) = w; } }
; template <class Epi, class Sched>
; DI void gemm_phase(LAS unsigned char* lds, const Gemm g, const Sched& S, const Epi& E) {
;     ...
;         if (!has_next) break;
; #pragma unroll
;         for (int a = 0; a < 2; ++a)
; #pragma unroll
;             for (int b = 0; b < 2; ++b)
; #pragma unroll
;                 for (int m = 0; m < 4; ++m)
; #pragma unroll
;                     for (int n = 0; n < 2; ++n) acc[a][b][m][n] = (f32x4){0.f, 0.f, 0.f, 0.f};
;         cur = nxt; cA = nA; cB = nB; ++ui;
;     }
;     PG8_WAIT_V(0);
;     if (wr == 0) PG8_BAR;
;     PG8_BAR;
	v_mov_b32_dpp v49, v243 quad_perm:[0,1,2,3] row_mask:0xf bank_mask:0x3
	global_store_dwordx4 v252, v[62:65], s[86:87] nt
	global_store_dwordx4 v253, v[46:49], s[86:87] nt
	v_cvt_pk_bf16_f32 v54, v54, v55
	v_cvt_pk_bf16_f32 v55, v56, v57
	v_cvt_pk_bf16_f32 v56, v50, v51
	v_cvt_pk_bf16_f32 v57, v52, v53
	v_cvt_pk_bf16_f32 v30, v30, v31
	v_cvt_pk_bf16_f32 v31, v32, v33
	v_cvt_pk_bf16_f32 v32, v26, v27
	v_cvt_pk_bf16_f32 v33, v28, v29
	v_mov_b32_dpp v240, v54 row_ror:8 row_mask:0xf bank_mask:0xf
	v_mov_b32_dpp v241, v55 row_ror:8 row_mask:0xf bank_mask:0xf
	v_mov_b32_dpp v242, v56 row_ror:8 row_mask:0xf bank_mask:0xf
	v_mov_b32_dpp v243, v57 row_ror:8 row_mask:0xf bank_mask:0xf
	v_mov_b32_dpp v54, v30 row_ror:8 row_mask:0xf bank_mask:0xc
	v_mov_b32_dpp v55, v31 row_ror:8 row_mask:0xf bank_mask:0xc
	v_mov_b32_dpp v56, v32 row_ror:8 row_mask:0xf bank_mask:0xc
	v_mov_b32_dpp v57, v33 row_ror:8 row_mask:0xf bank_mask:0xc
	v_mov_b32_dpp v30, v240 quad_perm:[0,1,2,3] row_mask:0xf bank_mask:0x3
	v_mov_b32_dpp v31, v241 quad_perm:[0,1,2,3] row_mask:0xf bank_mask:0x3
	v_mov_b32_dpp v32, v242 quad_perm:[0,1,2,3] row_mask:0xf bank_mask:0x3
	v_mov_b32_dpp v33, v243 quad_perm:[0,1,2,3] row_mask:0xf bank_mask:0x3
	global_store_dwordx4 v254, v[54:57], s[86:87] nt
	global_store_dwordx4 v255, v[30:33], s[86:87] nt
	v_cvt_pk_bf16_f32 v38, v38, v39
	v_cvt_pk_bf16_f32 v39, v40, v41
	v_cvt_pk_bf16_f32 v40, v34, v35
	v_cvt_pk_bf16_f32 v41, v36, v37
	v_cvt_pk_bf16_f32 v14, v14, v15
	v_cvt_pk_bf16_f32 v15, v16, v17
	v_cvt_pk_bf16_f32 v16, v10, v11
	v_cvt_pk_bf16_f32 v17, v12, v13
	v_mov_b32_dpp v240, v38 row_ror:8 row_mask:0xf bank_mask:0xf
	v_mov_b32_dpp v241, v39 row_ror:8 row_mask:0xf bank_mask:0xf
	v_mov_b32_dpp v242, v40 row_ror:8 row_mask:0xf bank_mask:0xf
	v_mov_b32_dpp v243, v41 row_ror:8 row_mask:0xf bank_mask:0xf
	v_mov_b32_dpp v38, v14 row_ror:8 row_mask:0xf bank_mask:0xc
	v_mov_b32_dpp v39, v15 row_ror:8 row_mask:0xf bank_mask:0xc
	v_mov_b32_dpp v40, v16 row_ror:8 row_mask:0xf bank_mask:0xc
	v_mov_b32_dpp v41, v17 row_ror:8 row_mask:0xf bank_mask:0xc
	v_mov_b32_dpp v14, v240 quad_perm:[0,1,2,3] row_mask:0xf bank_mask:0x3
	v_mov_b32_dpp v15, v241 quad_perm:[0,1,2,3] row_mask:0xf bank_mask:0x3
	v_mov_b32_dpp v16, v242 quad_perm:[0,1,2,3] row_mask:0xf bank_mask:0x3
	v_mov_b32_dpp v17, v243 quad_perm:[0,1,2,3] row_mask:0xf bank_mask:0x3
	global_store_dwordx4 v158, v[38:41], s[86:87] nt
	global_store_dwordx4 v159, v[14:17], s[86:87] nt
	v_cvt_pk_bf16_f32 v22, v22, v23
	v_cvt_pk_bf16_f32 v23, v24, v25
	v_cvt_pk_bf16_f32 v24, v18, v19
	v_cvt_pk_bf16_f32 v25, v20, v21
	v_cvt_pk_bf16_f32 v6, v6, v7
	v_cvt_pk_bf16_f32 v7, v8, v9
	v_cvt_pk_bf16_f32 v8, v2, v3
	v_cvt_pk_bf16_f32 v9, v4, v5
	v_mov_b32_dpp v240, v22 row_ror:8 row_mask:0xf bank_mask:0xf
	v_mov_b32_dpp v241, v23 row_ror:8 row_mask:0xf bank_mask:0xf
	v_mov_b32_dpp v242, v24 row_ror:8 row_mask:0xf bank_mask:0xf
	v_mov_b32_dpp v243, v25 row_ror:8 row_mask:0xf bank_mask:0xf
	v_mov_b32_dpp v22, v6 row_ror:8 row_mask:0xf bank_mask:0xc
	v_mov_b32_dpp v23, v7 row_ror:8 row_mask:0xf bank_mask:0xc
	v_mov_b32_dpp v24, v8 row_ror:8 row_mask:0xf bank_mask:0xc
	v_mov_b32_dpp v25, v9 row_ror:8 row_mask:0xf bank_mask:0xc
	v_mov_b32_dpp v6, v240 quad_perm:[0,1,2,3] row_mask:0xf bank_mask:0x3
	v_mov_b32_dpp v7, v241 quad_perm:[0,1,2,3] row_mask:0xf bank_mask:0x3
	v_mov_b32_dpp v8, v242 quad_perm:[0,1,2,3] row_mask:0xf bank_mask:0x3
	v_mov_b32_dpp v9, v243 quad_perm:[0,1,2,3] row_mask:0xf bank_mask:0x3
	global_store_dwordx4 v160, v[22:25], s[86:87] nt
	global_store_dwordx4 v161, v[6:9], s[86:87] nt
	s_cbranch_vccz .LBB0_123
	s_waitcnt vmcnt(0)
	s_cmpk_gt_u32 s12, 0xff
	s_cbranch_scc1 .LBB0_134
	s_barrier

; #define PG8_STAGE(bufoff, gbase, voff) do { _Pragma("unroll") for (int _i = 0; _i < 2; ++_i) \
;         __builtin_amdgcn_global_load_lds((const unsigned*)((const char*)(gbase) + (voff)[_i]), (LAS unsigned*)(lds + (bufoff) + ldsw + _i * 8192), 16, 0, 0); } while (0)
; #define PG8_LDA(dst, b, h) do { _Pragma("unroll") for (int m = 0; m < 4; ++m) _Pragma("unroll") for (int k = 0; k < 2; ++k) dst[m][k] = *(const LAS bf16x8*)(lds + PG8_SA(b, h) + aoff + m * 2048 + k * 1024); } while (0)
; #define PG8_LDB(dst, b, h) do { _Pragma("unroll") for (int n = 0; n < 2; ++n) _Pragma("unroll") for (int k = 0; k < 2; ++k) dst[n][k] = *(const LAS bf16x8*)(lds + PG8_SB(b, h) + boff + n * 2048 + k * 1024); } while (0)
; #define PG8_MMA(ai, bj, At, Bt) do { __builtin_amdgcn_s_setprio(1); _Pragma("unroll") for (int m = 0; m < 4; ++m) _Pragma("unroll") for (int n = 0; n < 2; ++n) _Pragma("unroll") for (int k = 0; k < 2; ++k) \
;         acc[ai][bj][m][n] = __builtin_amdgcn_mfma_f32_16x16x32_bf16(Bt[n][k], At[m][k], acc[ai][bj][m][n], 0, 0, 0); __builtin_amdgcn_s_setprio(0); } while (0)
; #define PG8_WAIT_L(n) asm volatile("s_waitcnt lgkmcnt(" #n ")" ::: "memory")
; #define PG8_BAR __builtin_amdgcn_s_barrier()
; #define PG8_SCHED __builtin_amdgcn_sched_barrier(0)
; template <class Epi, class Sched>
; DI void gemm_phase(LAS unsigned char* lds, const Gemm g, const Sched& S, const Epi& E) {
;     ...
;             PG8_LDB(B0, 0, 0); PG8_SCHED; PG8_LDA(At, 0, 0); PG8_STAGE(PG8_SA(1, 1), a1 + hstep, voffA);
;             PG8_WAIT_L(8); PG8_BAR; PG8_WAIT_L(0); PG8_MMA(0, 0, At, B0); PG8_BAR; PG8_SCHED;
;             PG8_LDB(B1, 0, 1); PG8_STAGE(PG8_SB(0, 0), b2, voffB);
;             PG8_BAR; PG8_WAIT_L(0); PG8_MMA(0, 1, At, B1); PG8_BAR;
;             PG8_LDA(At, 0, 1); PG8_STAGE(PG8_SA(0, 0), a2, voffA);
;             PG8_BAR; PG8_WAIT_L(0); PG8_MMA(1, 0, At, B0); PG8_BAR; PG8_SCHED;
.LBB0_1190:
	ds_read_b128 v[152:155], v149
	ds_read_b128 v[156:159], v149 offset:1024
	ds_read_b128 v[168:171], v149 offset:2048
	ds_read_b128 v[172:175], v149 offset:3072
	s_add_u32 s24, s22, 0xfffc0080
	s_addc_u32 s25, s23, -1
	s_cmp_eq_u32 s43, 12
	s_cselect_b32 s27, s17, s25
	s_cselect_b32 s26, s39, s24
	s_cselect_b32 s25, s11, s42
	s_cselect_b32 s24, s40, s41
	v_lshl_add_u64 v[160:161], s[22:23], 0, v[138:139]
	s_add_i32 m0, s9, 0xc000
	ds_read_b128 v[176:179], v150
	ds_read_b128 v[180:183], v150 offset:1024
	ds_read_b128 v[184:187], v150 offset:2048
	ds_read_b128 v[188:191], v150 offset:3072
	ds_read_b128 v[192:195], v150 offset:4096
	ds_read_b128 v[198:201], v150 offset:5120
	ds_read_b128 v[202:205], v150 offset:6144
	ds_read_b128 v[206:209], v150 offset:7168
	global_load_lds_dwordx4 v[160:161], off
	v_lshl_add_u64 v[160:161], s[22:23], 0, v[140:141]
	s_add_i32 m0, s9, 0xe000
	s_nop 0
	global_load_lds_dwordx4 v[160:161], off
	s_waitcnt lgkmcnt(8)
	s_barrier
	s_waitcnt lgkmcnt(0)
	s_setprio 1
	s_waitcnt lgkmcnt(0)
	v_mfma_f32_16x16x32_bf16 v[126:129], v[152:155], v[176:179], v[126:129]
	v_mfma_f32_16x16x32_bf16 v[122:125], v[168:171], v[176:179], v[122:125]
	v_mfma_f32_16x16x32_bf16 v[118:121], v[152:155], v[184:187], v[118:121]
	v_mfma_f32_16x16x32_bf16 v[114:117], v[168:171], v[184:187], v[114:117]
	v_mfma_f32_16x16x32_bf16 v[102:105], v[152:155], v[192:195], v[102:105]
	v_mfma_f32_16x16x32_bf16 v[98:101], v[168:171], v[192:195], v[98:101]
	v_mfma_f32_16x16x32_bf16 v[86:89], v[152:155], v[202:205], v[86:89]
	v_mfma_f32_16x16x32_bf16 v[82:85], v[168:171], v[202:205], v[82:85]
	v_mfma_f32_16x16x32_bf16 v[126:129], v[156:159], v[180:183], v[126:129]
	v_mfma_f32_16x16x32_bf16 v[122:125], v[172:175], v[180:183], v[122:125]
	v_mfma_f32_16x16x32_bf16 v[118:121], v[156:159], v[188:191], v[118:121]
	v_mfma_f32_16x16x32_bf16 v[114:117], v[172:175], v[188:191], v[114:117]
	v_mfma_f32_16x16x32_bf16 v[102:105], v[156:159], v[198:201], v[102:105]
	v_mfma_f32_16x16x32_bf16 v[98:101], v[172:175], v[198:201], v[98:101]
	v_mfma_f32_16x16x32_bf16 v[86:89], v[156:159], v[206:209], v[86:89]
	v_mfma_f32_16x16x32_bf16 v[82:85], v[172:175], v[206:209], v[82:85]
	s_setprio 0
	s_barrier
	s_add_i32 s47, s35, s12
	v_lshl_add_u64 v[160:161], s[24:25], 0, v[134:135]
	s_mov_b32 m0, s47
	ds_read_b128 v[210:213], v151
	ds_read_b128 v[214:217], v151 offset:1024
	ds_read_b128 v[218:221], v151 offset:2048
	ds_read_b128 v[222:225], v151 offset:3072
	global_load_lds_dwordx4 v[160:161], off
	v_lshl_add_u64 v[226:227], s[24:25], 0, v[130:131]
	s_add_i32 m0, s47, 0x2000
	s_nop 0
	global_load_lds_dwordx4 v[226:227], off
	s_barrier
	s_waitcnt lgkmcnt(0)
	s_setprio 1
	s_waitcnt lgkmcnt(0)
	v_mfma_f32_16x16x32_bf16 v[110:113], v[210:213], v[176:179], v[110:113]
	v_mfma_f32_16x16x32_bf16 v[106:109], v[218:221], v[176:179], v[106:109]
	v_mfma_f32_16x16x32_bf16 v[94:97], v[210:213], v[184:187], v[94:97]
	v_mfma_f32_16x16x32_bf16 v[90:93], v[218:221], v[184:187], v[90:93]
	v_mfma_f32_16x16x32_bf16 v[78:81], v[210:213], v[192:195], v[78:81]
	v_mfma_f32_16x16x32_bf16 v[74:77], v[218:221], v[192:195], v[74:77]
	v_mfma_f32_16x16x32_bf16 v[70:73], v[210:213], v[202:205], v[70:73]
	v_mfma_f32_16x16x32_bf16 v[66:69], v[218:221], v[202:205], v[66:69]
	v_mfma_f32_16x16x32_bf16 v[110:113], v[214:217], v[180:183], v[110:113]
	v_mfma_f32_16x16x32_bf16 v[106:109], v[222:225], v[180:183], v[106:109]
	v_mfma_f32_16x16x32_bf16 v[94:97], v[214:217], v[188:191], v[94:97]
	v_mfma_f32_16x16x32_bf16 v[90:93], v[222:225], v[188:191], v[90:93]
	v_mfma_f32_16x16x32_bf16 v[78:81], v[214:217], v[198:201], v[78:81]
	v_mfma_f32_16x16x32_bf16 v[74:77], v[222:225], v[198:201], v[74:77]
	v_mfma_f32_16x16x32_bf16 v[70:73], v[214:217], v[206:209], v[70:73]
	v_mfma_f32_16x16x32_bf16 v[66:69], v[222:225], v[206:209], v[66:69]
	s_setprio 0
	s_mov_b32 m0, s9
	v_lshl_add_u64 v[228:229], s[26:27], 0, v[136:137]
	s_barrier
	ds_read_b128 v[176:179], v150 offset:16384
	ds_read_b128 v[180:183], v150 offset:17408
	ds_read_b128 v[184:187], v150 offset:18432
	ds_read_b128 v[188:191], v150 offset:19456
	ds_read_b128 v[192:195], v150 offset:20480
	ds_read_b128 v[198:201], v150 offset:21504
	ds_read_b128 v[202:205], v150 offset:22528
	ds_read_b128 v[206:209], v150 offset:23552
	global_load_lds_dwordx4 v[228:229], off
	v_lshl_add_u64 v[230:231], s[26:27], 0, v[132:133]
	s_mov_b32 m0, s28
	s_nop 0
	global_load_lds_dwordx4 v[230:231], off
	s_barrier
	s_waitcnt lgkmcnt(0)
	s_setprio 1
	s_waitcnt lgkmcnt(0)
	v_mfma_f32_16x16x32_bf16 v[62:65], v[152:155], v[176:179], v[62:65]
	v_mfma_f32_16x16x32_bf16 v[58:61], v[168:171], v[176:179], v[58:61]
	v_mfma_f32_16x16x32_bf16 v[54:57], v[152:155], v[184:187], v[54:57]
	v_mfma_f32_16x16x32_bf16 v[50:53], v[168:171], v[184:187], v[50:53]
	v_mfma_f32_16x16x32_bf16 v[38:41], v[152:155], v[192:195], v[38:41]
	v_mfma_f32_16x16x32_bf16 v[34:37], v[168:171], v[192:195], v[34:37]
	v_mfma_f32_16x16x32_bf16 v[22:25], v[152:155], v[202:205], v[22:25]
	v_mfma_f32_16x16x32_bf16 v[18:21], v[168:171], v[202:205], v[18:21]
	v_mfma_f32_16x16x32_bf16 v[62:65], v[156:159], v[180:183], v[62:65]
	v_mfma_f32_16x16x32_bf16 v[58:61], v[172:175], v[180:183], v[58:61]
	v_mfma_f32_16x16x32_bf16 v[54:57], v[156:159], v[188:191], v[54:57]
	v_mfma_f32_16x16x32_bf16 v[50:53], v[172:175], v[188:191], v[50:53]
	v_mfma_f32_16x16x32_bf16 v[38:41], v[156:159], v[198:201], v[38:41]
	v_mfma_f32_16x16x32_bf16 v[34:37], v[172:175], v[198:201], v[34:37]
	v_mfma_f32_16x16x32_bf16 v[22:25], v[156:159], v[206:209], v[22:25]
	v_mfma_f32_16x16x32_bf16 v[18:21], v[172:175], v[206:209], v[18:21]
	s_setprio 0
	s_barrier
; #define PG8_STAGE(bufoff, gbase, voff) do { _Pragma("unroll") for (int _i = 0; _i < 2; ++_i) \
;         __builtin_amdgcn_global_load_lds((const unsigned*)((const char*)(gbase) + (voff)[_i]), (LAS unsigned*)(lds + (bufoff) + ldsw + _i * 8192), 16, 0, 0); } while (0)
; #define PG8_LDA(dst, b, h) do { _Pragma("unroll") for (int m = 0; m < 4; ++m) _Pragma("unroll") for (int k = 0; k < 2; ++k) dst[m][k] = *(const LAS bf16x8*)(lds + PG8_SA(b, h) + aoff + m * 2048 + k * 1024); } while (0)
; #define PG8_LDB(dst, b, h) do { _Pragma("unroll") for (int n = 0; n < 2; ++n) _Pragma("unroll") for (int k = 0; k < 2; ++k) dst[n][k] = *(const LAS bf16x8*)(lds + PG8_SB(b, h) + boff + n * 2048 + k * 1024); } while (0)
; #define PG8_MMA(ai, bj, At, Bt) do { __builtin_amdgcn_s_setprio(1); _Pragma("unroll") for (int m = 0; m < 4; ++m) _Pragma("unroll") for (int n = 0; n < 2; ++n) _Pragma("unroll") for (int k = 0; k < 2; ++k) \
;         acc[ai][bj][m][n] = __builtin_amdgcn_mfma_f32_16x16x32_bf16(Bt[n][k], At[m][k], acc[ai][bj][m][n], 0, 0, 0); __builtin_amdgcn_s_setprio(0); } while (0)
; #define PG8_WAIT_V(n) asm volatile("s_waitcnt vmcnt(" #n ")" ::: "memory")
; #define PG8_WAIT_L(n) asm volatile("s_waitcnt lgkmcnt(" #n ")" ::: "memory")
; #define PG8_BAR __builtin_amdgcn_s_barrier()
; #define PG8_SCHED __builtin_amdgcn_sched_barrier(0)
; template <class Epi, class Sched>
; DI void gemm_phase(LAS unsigned char* lds, const Gemm g, const Sched& S, const Epi& E) {
;     ...
;             PG8_BAR; PG8_WAIT_L(0); PG8_MMA(1, 0, At, B0); PG8_BAR; PG8_SCHED;
;             PG8_STAGE(PG8_SB(0, 1), b2 + hstep, voffB);
;             PG8_WAIT_V(6); PG8_BAR; PG8_MMA(1, 1, At, B1); PG8_BAR;
;             PG8_LDB(B0, 1, 0); PG8_SCHED; PG8_LDA(At, 1, 0); PG8_STAGE(PG8_SA(0, 1), a2 + hstep, voffA);
;             PG8_WAIT_L(8); PG8_BAR; PG8_WAIT_L(0); PG8_MMA(0, 0, At, B0); PG8_BAR; PG8_SCHED;
;             PG8_LDB(B1, 1, 1); PG8_STAGE(PG8_SB(1, 0), b3, voffB);
;             PG8_BAR; PG8_WAIT_L(0); PG8_MMA(0, 1, At, B1); PG8_BAR;
	s_add_u32 s54, s24, 0x10000
	s_addc_u32 s55, s25, 0
	s_add_i32 s47, s36, s12
	v_lshl_add_u64 v[152:153], s[54:55], 0, v[134:135]
	s_mov_b32 m0, s47
	s_nop 0
	global_load_lds_dwordx4 v[152:153], off
	v_lshl_add_u64 v[152:153], s[54:55], 0, v[130:131]
	s_add_i32 m0, s47, 0x2000
	s_nop 0
	global_load_lds_dwordx4 v[152:153], off
	s_waitcnt vmcnt(6)
	s_barrier
	s_setprio 1
	v_mfma_f32_16x16x32_bf16 v[46:49], v[210:213], v[176:179], v[46:49]
	v_mfma_f32_16x16x32_bf16 v[42:45], v[218:221], v[176:179], v[42:45]
	v_mfma_f32_16x16x32_bf16 v[30:33], v[210:213], v[184:187], v[30:33]
	v_mfma_f32_16x16x32_bf16 v[26:29], v[218:221], v[184:187], v[26:29]
	v_mfma_f32_16x16x32_bf16 v[14:17], v[210:213], v[192:195], v[14:17]
	v_mfma_f32_16x16x32_bf16 v[10:13], v[218:221], v[192:195], v[10:13]
	v_mfma_f32_16x16x32_bf16 v[6:9], v[210:213], v[202:205], v[6:9]
	v_mfma_f32_16x16x32_bf16 v[2:5], v[218:221], v[202:205], v[2:5]
	v_mfma_f32_16x16x32_bf16 v[46:49], v[214:217], v[180:183], v[46:49]
	v_mfma_f32_16x16x32_bf16 v[42:45], v[222:225], v[180:183], v[42:45]
	v_mfma_f32_16x16x32_bf16 v[30:33], v[214:217], v[188:191], v[30:33]
	v_mfma_f32_16x16x32_bf16 v[26:29], v[222:225], v[188:191], v[26:29]
	v_mfma_f32_16x16x32_bf16 v[14:17], v[214:217], v[198:201], v[14:17]
	v_mfma_f32_16x16x32_bf16 v[10:13], v[222:225], v[198:201], v[10:13]
	v_mfma_f32_16x16x32_bf16 v[6:9], v[214:217], v[206:209], v[6:9]
	v_mfma_f32_16x16x32_bf16 v[2:5], v[222:225], v[206:209], v[2:5]
	s_setprio 0
	s_add_i32 s47, 0, 0x18000
	v_add_u32_e32 v165, s47, v147
	s_barrier
	ds_read_b128 v[152:155], v165
	ds_read_b128 v[156:159], v165 offset:1024
	ds_read_b128 v[168:171], v165 offset:2048
	ds_read_b128 v[172:175], v165 offset:3072
	s_add_u32 s26, s26, 0x40000
	s_addc_u32 s27, s27, 0
	s_mov_b32 m0, s29
	v_lshl_add_u64 v[210:211], s[26:27], 0, v[136:137]
	ds_read_b128 v[176:179], v150 offset:32768
	ds_read_b128 v[180:183], v150 offset:33792
	ds_read_b128 v[184:187], v150 offset:34816
	ds_read_b128 v[188:191], v150 offset:35840
	ds_read_b128 v[192:195], v150 offset:36864
	ds_read_b128 v[198:201], v150 offset:37888
	ds_read_b128 v[202:205], v150 offset:38912
	ds_read_b128 v[206:209], v150 offset:39936
	global_load_lds_dwordx4 v[210:211], off
	v_lshl_add_u64 v[210:211], s[26:27], 0, v[132:133]
	s_mov_b32 m0, s30
	s_nop 0
	global_load_lds_dwordx4 v[210:211], off
	s_waitcnt lgkmcnt(8)
	s_barrier
	s_waitcnt lgkmcnt(0)
	s_setprio 1
	s_waitcnt lgkmcnt(0)
	v_mfma_f32_16x16x32_bf16 v[126:129], v[152:155], v[176:179], v[126:129]
	v_mfma_f32_16x16x32_bf16 v[122:125], v[168:171], v[176:179], v[122:125]
	v_mfma_f32_16x16x32_bf16 v[118:121], v[152:155], v[184:187], v[118:121]
	v_mfma_f32_16x16x32_bf16 v[114:117], v[168:171], v[184:187], v[114:117]
	v_mfma_f32_16x16x32_bf16 v[102:105], v[152:155], v[192:195], v[102:105]
	v_mfma_f32_16x16x32_bf16 v[98:101], v[168:171], v[192:195], v[98:101]
	v_mfma_f32_16x16x32_bf16 v[86:89], v[152:155], v[202:205], v[86:89]
	v_mfma_f32_16x16x32_bf16 v[82:85], v[168:171], v[202:205], v[82:85]
	v_mfma_f32_16x16x32_bf16 v[126:129], v[156:159], v[180:183], v[126:129]
	v_mfma_f32_16x16x32_bf16 v[122:125], v[172:175], v[180:183], v[122:125]
	v_mfma_f32_16x16x32_bf16 v[118:121], v[156:159], v[188:191], v[118:121]
	v_mfma_f32_16x16x32_bf16 v[114:117], v[172:175], v[188:191], v[114:117]
	v_mfma_f32_16x16x32_bf16 v[102:105], v[156:159], v[198:201], v[102:105]
	v_mfma_f32_16x16x32_bf16 v[98:101], v[172:175], v[198:201], v[98:101]
	v_mfma_f32_16x16x32_bf16 v[86:89], v[156:159], v[206:209], v[86:89]
	v_mfma_f32_16x16x32_bf16 v[82:85], v[172:175], v[206:209], v[82:85]
	s_setprio 0
	s_barrier
	s_add_i32 s26, 0, 0x1c000
	s_add_i32 s27, s47, s12
	v_add_u32_e32 v165, s26, v147
	v_lshl_add_u64 v[160:161], v[160:161], 0, s[6:7]
	s_mov_b32 m0, s27
	ds_read_b128 v[210:213], v165
	ds_read_b128 v[214:217], v165 offset:1024
	ds_read_b128 v[218:221], v165 offset:2048
	ds_read_b128 v[222:225], v165 offset:3072
	global_load_lds_dwordx4 v[160:161], off
	v_lshl_add_u64 v[160:161], v[226:227], 0, s[6:7]
	s_add_i32 m0, s27, 0x2000
	s_nop 0
	global_load_lds_dwordx4 v[160:161], off
	s_barrier
	s_waitcnt lgkmcnt(0)
	s_setprio 1
	s_waitcnt lgkmcnt(0)
	v_mfma_f32_16x16x32_bf16 v[110:113], v[210:213], v[176:179], v[110:113]
	v_mfma_f32_16x16x32_bf16 v[106:109], v[218:221], v[176:179], v[106:109]
	v_mfma_f32_16x16x32_bf16 v[94:97], v[210:213], v[184:187], v[94:97]
	v_mfma_f32_16x16x32_bf16 v[90:93], v[218:221], v[184:187], v[90:93]
	v_mfma_f32_16x16x32_bf16 v[78:81], v[210:213], v[192:195], v[78:81]
	v_mfma_f32_16x16x32_bf16 v[74:77], v[218:221], v[192:195], v[74:77]
	v_mfma_f32_16x16x32_bf16 v[70:73], v[210:213], v[202:205], v[70:73]
	v_mfma_f32_16x16x32_bf16 v[66:69], v[218:221], v[202:205], v[66:69]
	v_mfma_f32_16x16x32_bf16 v[110:113], v[214:217], v[180:183], v[110:113]
	v_mfma_f32_16x16x32_bf16 v[106:109], v[222:225], v[180:183], v[106:109]
	v_mfma_f32_16x16x32_bf16 v[94:97], v[214:217], v[188:191], v[94:97]
	v_mfma_f32_16x16x32_bf16 v[90:93], v[222:225], v[188:191], v[90:93]
	v_mfma_f32_16x16x32_bf16 v[78:81], v[214:217], v[198:201], v[78:81]
	v_mfma_f32_16x16x32_bf16 v[74:77], v[222:225], v[198:201], v[74:77]
	v_mfma_f32_16x16x32_bf16 v[70:73], v[214:217], v[206:209], v[70:73]
	v_mfma_f32_16x16x32_bf16 v[66:69], v[222:225], v[206:209], v[66:69]
	s_setprio 0
	s_mov_b32 m0, s33
	v_lshl_add_u64 v[160:161], v[228:229], 0, s[6:7]
	s_barrier
	ds_read_b128 v[176:179], v150 offset:49152
	ds_read_b128 v[180:183], v150 offset:50176
	ds_read_b128 v[184:187], v150 offset:51200
	ds_read_b128 v[188:191], v150 offset:52224
	ds_read_b128 v[192:195], v150 offset:53248
	ds_read_b128 v[198:201], v150 offset:54272
	ds_read_b128 v[202:205], v150 offset:55296
	ds_read_b128 v[206:209], v150 offset:56320
	global_load_lds_dwordx4 v[160:161], off
	v_lshl_add_u64 v[160:161], v[230:231], 0, s[6:7]
	s_mov_b32 m0, s34
	s_nop 0
	global_load_lds_dwordx4 v[160:161], off
	s_barrier
; DI unsigned pk_bf16(float a, float b) { f32x2 v = {a, b}; bf2_t r = __builtin_convertvector(v, bf2_t); return __builtin_bit_cast(unsigned, r); }
; #define PG8_STAGE(bufoff, gbase, voff) do { _Pragma("unroll") for (int _i = 0; _i < 2; ++_i) \
;         __builtin_amdgcn_global_load_lds((const unsigned*)((const char*)(gbase) + (voff)[_i]), (LAS unsigned*)(lds + (bufoff) + ldsw + _i * 8192), 16, 0, 0); } while (0)
; #define PG8_LDA(dst, b, h) do { _Pragma("unroll") for (int m = 0; m < 4; ++m) _Pragma("unroll") for (int k = 0; k < 2; ++k) dst[m][k] = *(const LAS bf16x8*)(lds + PG8_SA(b, h) + aoff + m * 2048 + k * 1024); } while (0)
; #define PG8_MMA(ai, bj, At, Bt) do { __builtin_amdgcn_s_setprio(1); _Pragma("unroll") for (int m = 0; m < 4; ++m) _Pragma("unroll") for (int n = 0; n < 2; ++n) _Pragma("unroll") for (int k = 0; k < 2; ++k) \
;         acc[ai][bj][m][n] = __builtin_amdgcn_mfma_f32_16x16x32_bf16(Bt[n][k], At[m][k], acc[ai][bj][m][n], 0, 0, 0); __builtin_amdgcn_s_setprio(0); } while (0)
; #define PG8_WAIT_V(n) asm volatile("s_waitcnt vmcnt(" #n ")" ::: "memory")
; #define PG8_BAR __builtin_amdgcn_s_barrier()
;     DI void operator()(const f32x4 (&acc)[2][2][4][2], const Unit& u, int wr, int wc, int fr, int fq) const {
;         const int row0 = u.pm * BM + wr * 64 + fr, col0 = u.pn * BM + wc * 32 + 8 * fq;
; #pragma unroll
;         for (int ai = 0; ai < 2; ++ai)
; #pragma unroll
;             for (int m = 0; m < 4; ++m) { bf16_t* rowp = O + (size_t)(row0 + ai * HALF + m * 16) * ldc + col0;
; #pragma unroll
;                 for (int bj = 0; bj < 2; ++bj) { const f32x4 v0 = acc[ai][bj][m][0], v1 = acc[ai][bj][m][1];
;                     u32x4 w; w.x = pk_bf16(v0[0], v0[1]); w.y = pk_bf16(v0[2], v0[3]); w.z = pk_bf16(v1[0], v1[1]); w.w = pk_bf16(v1[2], v1[3]);
;                     *(u32x4*)(rowp + bj * HALF) = w; } }
; template <class Epi, class Sched>
; DI void gemm_phase(LAS unsigned char* lds, const Gemm g, const Sched& S, const Epi& E) {
;     ...
;             PG8_BAR; PG8_WAIT_L(0); PG8_MMA(0, 1, At, B1); PG8_BAR;
;             PG8_LDA(At, 1, 1); PG8_STAGE(PG8_SA(1, 0), a3, voffA);
;             PG8_BAR; PG8_WAIT_L(0); PG8_MMA(1, 0, At, B0); PG8_BAR; PG8_SCHED;
;             PG8_STAGE(PG8_SB(1, 1), b3 + hstep, voffB);
;             PG8_WAIT_V(6); PG8_BAR; PG8_MMA(1, 1, At, B1); PG8_BAR;
;         }
;         E(acc, cur, wr, wc, fr, fq);
	s_waitcnt lgkmcnt(0)
	s_setprio 1
	s_waitcnt lgkmcnt(0)
	v_mfma_f32_16x16x32_bf16 v[62:65], v[152:155], v[176:179], v[62:65]
	v_mfma_f32_16x16x32_bf16 v[58:61], v[168:171], v[176:179], v[58:61]
	v_mfma_f32_16x16x32_bf16 v[54:57], v[152:155], v[184:187], v[54:57]
	v_mfma_f32_16x16x32_bf16 v[50:53], v[168:171], v[184:187], v[50:53]
	v_mfma_f32_16x16x32_bf16 v[38:41], v[152:155], v[192:195], v[38:41]
	v_mfma_f32_16x16x32_bf16 v[34:37], v[168:171], v[192:195], v[34:37]
	v_mfma_f32_16x16x32_bf16 v[22:25], v[152:155], v[202:205], v[22:25]
	v_mfma_f32_16x16x32_bf16 v[18:21], v[168:171], v[202:205], v[18:21]
	v_mfma_f32_16x16x32_bf16 v[62:65], v[156:159], v[180:183], v[62:65]
	v_mfma_f32_16x16x32_bf16 v[58:61], v[172:175], v[180:183], v[58:61]
	v_mfma_f32_16x16x32_bf16 v[54:57], v[156:159], v[188:191], v[54:57]
	v_mfma_f32_16x16x32_bf16 v[50:53], v[172:175], v[188:191], v[50:53]
	v_mfma_f32_16x16x32_bf16 v[38:41], v[156:159], v[198:201], v[38:41]
	v_mfma_f32_16x16x32_bf16 v[34:37], v[172:175], v[198:201], v[34:37]
	v_mfma_f32_16x16x32_bf16 v[22:25], v[156:159], v[206:209], v[22:25]
	v_mfma_f32_16x16x32_bf16 v[18:21], v[172:175], v[206:209], v[18:21]
	s_setprio 0
	s_barrier
	s_add_u32 s24, s24, 0x10080
	s_addc_u32 s25, s25, 0
	s_add_i32 s26, s26, s12
	v_lshl_add_u64 v[152:153], s[24:25], 0, v[134:135]
	s_mov_b32 m0, s26
	s_nop 0
	global_load_lds_dwordx4 v[152:153], off
	v_lshl_add_u64 v[152:153], s[24:25], 0, v[130:131]
	s_add_i32 m0, s26, 0x2000
	s_nop 0
	global_load_lds_dwordx4 v[152:153], off
	s_waitcnt vmcnt(6)
	s_barrier
	s_setprio 1
	v_mfma_f32_16x16x32_bf16 v[46:49], v[210:213], v[176:179], v[46:49]
	v_mfma_f32_16x16x32_bf16 v[42:45], v[218:221], v[176:179], v[42:45]
	v_mfma_f32_16x16x32_bf16 v[30:33], v[210:213], v[184:187], v[30:33]
	v_mfma_f32_16x16x32_bf16 v[26:29], v[218:221], v[184:187], v[26:29]
	v_mfma_f32_16x16x32_bf16 v[14:17], v[210:213], v[192:195], v[14:17]
	v_mfma_f32_16x16x32_bf16 v[10:13], v[218:221], v[192:195], v[10:13]
	v_mfma_f32_16x16x32_bf16 v[6:9], v[210:213], v[202:205], v[6:9]
	v_mfma_f32_16x16x32_bf16 v[2:5], v[218:221], v[202:205], v[2:5]
	v_mfma_f32_16x16x32_bf16 v[46:49], v[214:217], v[180:183], v[46:49]
	v_mfma_f32_16x16x32_bf16 v[42:45], v[222:225], v[180:183], v[42:45]
	v_mfma_f32_16x16x32_bf16 v[30:33], v[214:217], v[188:191], v[30:33]
	v_mfma_f32_16x16x32_bf16 v[26:29], v[222:225], v[188:191], v[26:29]
	v_mfma_f32_16x16x32_bf16 v[14:17], v[214:217], v[198:201], v[14:17]
	v_mfma_f32_16x16x32_bf16 v[10:13], v[222:225], v[198:201], v[10:13]
	v_mfma_f32_16x16x32_bf16 v[6:9], v[214:217], v[206:209], v[6:9]
	v_mfma_f32_16x16x32_bf16 v[2:5], v[222:225], v[206:209], v[2:5]
	s_setprio 0
	s_add_i32 s43, s43, 2
	s_add_u32 s22, s22, 0x100
	s_addc_u32 s23, s23, 0
	s_add_u32 s41, s41, 0x100
	s_addc_u32 s42, s42, 0
	s_cmp_gt_u32 s43, 13
	s_barrier
	s_cbranch_scc0 .LBB0_1190
	v_and_b32_e32 v152, 8, v146
	v_sub_u32_e32 v153, v146, v152
	v_lshl_add_u32 v153, s8, 8, v153
	v_lshl_add_u32 v152, v152, 2, v148
	v_lshl_or_b32 v152, s38, 8, v152
	v_mul_u32_u24_e32 v153, 0x3000, v153
	v_lshl_add_u32 v244, v152, 1, v153
	v_add_u32_e32 v245, 0x18000, v244
	v_add_u32_e32 v246, 0x30000, v244
	v_add_u32_e32 v247, 0x48000, v244
	v_add_u32_e32 v248, 0x60000, v244
	v_add_u32_e32 v249, 0x78000, v244
	v_add_u32_e32 v250, 0x90000, v244
	v_add_u32_e32 v251, 0xa8000, v244
	v_add_u32_e32 v252, 0x180000, v244
	v_add_u32_e32 v253, 0x198000, v244
	v_add_u32_e32 v254, 0x1b0000, v244
	v_add_u32_e32 v255, 0x1c8000, v244
	v_add_u32_e32 v154, 0x1e0000, v244
	v_add_u32_e32 v155, 0x1f8000, v244
	v_add_u32_e32 v156, 0x210000, v244
	v_add_u32_e32 v157, 0x228000, v244
	s_and_b64 vcc, exec, s[4:5]
	s_mov_b32 s38, s10
	s_mov_b32 s8, s16
	s_mov_b64 s[24:25], s[20:21]
	s_mov_b64 s[22:23], s[18:19]
	v_cvt_pk_bf16_f32 v126, v126, v127
	v_cvt_pk_bf16_f32 v127, v128, v129
	v_cvt_pk_bf16_f32 v128, v122, v123
	v_cvt_pk_bf16_f32 v129, v124, v125
	v_cvt_pk_bf16_f32 v110, v110, v111
	v_cvt_pk_bf16_f32 v111, v112, v113
	v_cvt_pk_bf16_f32 v112, v106, v107
	v_cvt_pk_bf16_f32 v113, v108, v109
	v_mov_b32_dpp v240, v126 row_ror:8 row_mask:0xf bank_mask:0xf
	v_mov_b32_dpp v241, v127 row_ror:8 row_mask:0xf bank_mask:0xf
	v_mov_b32_dpp v242, v128 row_ror:8 row_mask:0xf bank_mask:0xf
	v_mov_b32_dpp v243, v129 row_ror:8 row_mask:0xf bank_mask:0xf
	v_mov_b32_dpp v126, v110 row_ror:8 row_mask:0xf bank_mask:0xc
	v_mov_b32_dpp v127, v111 row_ror:8 row_mask:0xf bank_mask:0xc
	v_mov_b32_dpp v128, v112 row_ror:8 row_mask:0xf bank_mask:0xc
	v_mov_b32_dpp v129, v113 row_ror:8 row_mask:0xf bank_mask:0xc
	v_mov_b32_dpp v110, v240 quad_perm:[0,1,2,3] row_mask:0xf bank_mask:0x3
	v_mov_b32_dpp v111, v241 quad_perm:[0,1,2,3] row_mask:0xf bank_mask:0x3
	v_mov_b32_dpp v112, v242 quad_perm:[0,1,2,3] row_mask:0xf bank_mask:0x3
	v_mov_b32_dpp v113, v243 quad_perm:[0,1,2,3] row_mask:0xf bank_mask:0x3
	global_store_dwordx4 v244, v[126:129], s[86:87] nt
	global_store_dwordx4 v245, v[110:113], s[86:87] nt
	v_cvt_pk_bf16_f32 v118, v118, v119
	v_cvt_pk_bf16_f32 v119, v120, v121
	v_cvt_pk_bf16_f32 v120, v114, v115
	v_cvt_pk_bf16_f32 v121, v116, v117
	v_cvt_pk_bf16_f32 v94, v94, v95
	v_cvt_pk_bf16_f32 v95, v96, v97
	v_cvt_pk_bf16_f32 v96, v90, v91
	v_cvt_pk_bf16_f32 v97, v92, v93
	v_mov_b32_dpp v240, v118 row_ror:8 row_mask:0xf bank_mask:0xf
	v_mov_b32_dpp v241, v119 row_ror:8 row_mask:0xf bank_mask:0xf
	v_mov_b32_dpp v242, v120 row_ror:8 row_mask:0xf bank_mask:0xf
	v_mov_b32_dpp v243, v121 row_ror:8 row_mask:0xf bank_mask:0xf
	v_mov_b32_dpp v118, v94 row_ror:8 row_mask:0xf bank_mask:0xc
	v_mov_b32_dpp v119, v95 row_ror:8 row_mask:0xf bank_mask:0xc
	v_mov_b32_dpp v120, v96 row_ror:8 row_mask:0xf bank_mask:0xc
; DI unsigned pk_bf16(float a, float b) { f32x2 v = {a, b}; bf2_t r = __builtin_convertvector(v, bf2_t); return __builtin_bit_cast(unsigned, r); }
;     DI void operator()(const f32x4 (&acc)[2][2][4][2], const Unit& u, int wr, int wc, int fr, int fq) const {
;     ...
;             for (int m = 0; m < 4; ++m) { bf16_t* rowp = O + (size_t)(row0 + ai * HALF + m * 16) * ldc + col0;
; #pragma unroll
;                 for (int bj = 0; bj < 2; ++bj) { const f32x4 v0 = acc[ai][bj][m][0], v1 = acc[ai][bj][m][1];
;                     u32x4 w; w.x = pk_bf16(v0[0], v0[1]); w.y = pk_bf16(v0[2], v0[3]); w.z = pk_bf16(v1[0], v1[1]); w.w = pk_bf16(v1[2], v1[3]);
;                     *(u32x4*)(rowp + bj * HALF) = w; } }
	v_mov_b32_dpp v121, v97 row_ror:8 row_mask:0xf bank_mask:0xc
	v_mov_b32_dpp v94, v240 quad_perm:[0,1,2,3] row_mask:0xf bank_mask:0x3
	v_mov_b32_dpp v95, v241 quad_perm:[0,1,2,3] row_mask:0xf bank_mask:0x3
	v_mov_b32_dpp v96, v242 quad_perm:[0,1,2,3] row_mask:0xf bank_mask:0x3
	v_mov_b32_dpp v97, v243 quad_perm:[0,1,2,3] row_mask:0xf bank_mask:0x3
	global_store_dwordx4 v246, v[118:121], s[86:87] nt
	global_store_dwordx4 v247, v[94:97], s[86:87] nt
	v_cvt_pk_bf16_f32 v102, v102, v103
	v_cvt_pk_bf16_f32 v103, v104, v105
	v_cvt_pk_bf16_f32 v104, v98, v99
	v_cvt_pk_bf16_f32 v105, v100, v101
	v_cvt_pk_bf16_f32 v78, v78, v79
	v_cvt_pk_bf16_f32 v79, v80, v81
	v_cvt_pk_bf16_f32 v80, v74, v75
	v_cvt_pk_bf16_f32 v81, v76, v77
	v_mov_b32_dpp v240, v102 row_ror:8 row_mask:0xf bank_mask:0xf
	v_mov_b32_dpp v241, v103 row_ror:8 row_mask:0xf bank_mask:0xf
	v_mov_b32_dpp v242, v104 row_ror:8 row_mask:0xf bank_mask:0xf
	v_mov_b32_dpp v243, v105 row_ror:8 row_mask:0xf bank_mask:0xf
	v_mov_b32_dpp v102, v78 row_ror:8 row_mask:0xf bank_mask:0xc
	v_mov_b32_dpp v103, v79 row_ror:8 row_mask:0xf bank_mask:0xc
	v_mov_b32_dpp v104, v80 row_ror:8 row_mask:0xf bank_mask:0xc
	v_mov_b32_dpp v105, v81 row_ror:8 row_mask:0xf bank_mask:0xc
	v_mov_b32_dpp v78, v240 quad_perm:[0,1,2,3] row_mask:0xf bank_mask:0x3
	v_mov_b32_dpp v79, v241 quad_perm:[0,1,2,3] row_mask:0xf bank_mask:0x3
	v_mov_b32_dpp v80, v242 quad_perm:[0,1,2,3] row_mask:0xf bank_mask:0x3
	v_mov_b32_dpp v81, v243 quad_perm:[0,1,2,3] row_mask:0xf bank_mask:0x3
	global_store_dwordx4 v248, v[102:105], s[86:87] nt
	global_store_dwordx4 v249, v[78:81], s[86:87] nt
	v_cvt_pk_bf16_f32 v86, v86, v87
	v_cvt_pk_bf16_f32 v87, v88, v89
	v_cvt_pk_bf16_f32 v88, v82, v83
	v_cvt_pk_bf16_f32 v89, v84, v85
	v_cvt_pk_bf16_f32 v70, v70, v71
	v_cvt_pk_bf16_f32 v71, v72, v73
	v_cvt_pk_bf16_f32 v72, v66, v67
	v_cvt_pk_bf16_f32 v73, v68, v69
	v_mov_b32_dpp v240, v86 row_ror:8 row_mask:0xf bank_mask:0xf
	v_mov_b32_dpp v241, v87 row_ror:8 row_mask:0xf bank_mask:0xf
	v_mov_b32_dpp v242, v88 row_ror:8 row_mask:0xf bank_mask:0xf
	v_mov_b32_dpp v243, v89 row_ror:8 row_mask:0xf bank_mask:0xf
	v_mov_b32_dpp v86, v70 row_ror:8 row_mask:0xf bank_mask:0xc
	v_mov_b32_dpp v87, v71 row_ror:8 row_mask:0xf bank_mask:0xc
	v_mov_b32_dpp v88, v72 row_ror:8 row_mask:0xf bank_mask:0xc
	v_mov_b32_dpp v89, v73 row_ror:8 row_mask:0xf bank_mask:0xc
	v_mov_b32_dpp v70, v240 quad_perm:[0,1,2,3] row_mask:0xf bank_mask:0x3
	v_mov_b32_dpp v71, v241 quad_perm:[0,1,2,3] row_mask:0xf bank_mask:0x3
	v_mov_b32_dpp v72, v242 quad_perm:[0,1,2,3] row_mask:0xf bank_mask:0x3
	v_mov_b32_dpp v73, v243 quad_perm:[0,1,2,3] row_mask:0xf bank_mask:0x3
	global_store_dwordx4 v250, v[86:89], s[86:87] nt
	global_store_dwordx4 v251, v[70:73], s[86:87] nt
	v_cvt_pk_bf16_f32 v62, v62, v63
	v_cvt_pk_bf16_f32 v63, v64, v65
	v_cvt_pk_bf16_f32 v64, v58, v59
	v_cvt_pk_bf16_f32 v65, v60, v61
	v_cvt_pk_bf16_f32 v46, v46, v47
	v_cvt_pk_bf16_f32 v47, v48, v49
	v_cvt_pk_bf16_f32 v48, v42, v43
	v_cvt_pk_bf16_f32 v49, v44, v45
	v_mov_b32_dpp v240, v62 row_ror:8 row_mask:0xf bank_mask:0xf
	v_mov_b32_dpp v241, v63 row_ror:8 row_mask:0xf bank_mask:0xf
	v_mov_b32_dpp v242, v64 row_ror:8 row_mask:0xf bank_mask:0xf
	v_mov_b32_dpp v243, v65 row_ror:8 row_mask:0xf bank_mask:0xf
	v_mov_b32_dpp v62, v46 row_ror:8 row_mask:0xf bank_mask:0xc
	v_mov_b32_dpp v63, v47 row_ror:8 row_mask:0xf bank_mask:0xc
	v_mov_b32_dpp v64, v48 row_ror:8 row_mask:0xf bank_mask:0xc
	v_mov_b32_dpp v65, v49 row_ror:8 row_mask:0xf bank_mask:0xc
	v_mov_b32_dpp v46, v240 quad_perm:[0,1,2,3] row_mask:0xf bank_mask:0x3
	v_mov_b32_dpp v47, v241 quad_perm:[0,1,2,3] row_mask:0xf bank_mask:0x3
	v_mov_b32_dpp v48, v242 quad_perm:[0,1,2,3] row_mask:0xf bank_mask:0x3
; DI unsigned pk_bf16(float a, float b) { f32x2 v = {a, b}; bf2_t r = __builtin_convertvector(v, bf2_t); return __builtin_bit_cast(unsigned, r); }
; #define PG8_WAIT_V(n) asm volatile("s_waitcnt vmcnt(" #n ")" ::: "memory")
; #define PG8_BAR __builtin_amdgcn_s_barrier()
;     DI void operator()(const f32x4 (&acc)[2][2][4][2], const Unit& u, int wr, int wc, int fr, int fq) const {
;     ...
;             for (int m = 0; m < 4; ++m) { bf16_t* rowp = O + (size_t)(row0 + ai * HALF + m * 16) * ldc + col0;
; #pragma unroll
;                 for (int bj = 0; bj < 2; ++bj) { const f32x4 v0 = acc[ai][bj][m][0], v1 = acc[ai][bj][m][1];
;                     u32x4 w; w.x = pk_bf16(v0[0], v0[1]); w.y = pk_bf16(v0[2], v0[3]); w.z = pk_bf16(v1[0], v1[1]); w.w = pk_bf16(v1[2], v1[3]);
;                     *(u32x4*)(rowp + bj * HALF) = w; } }
; template <class Epi, class Sched>
; DI void gemm_phase(LAS unsigned char* lds, const Gemm g, const Sched& S, const Epi& E) {
;     ...
;         if (!has_next) break;
; #pragma unroll
;         for (int a = 0; a < 2; ++a)
; #pragma unroll
;             for (int b = 0; b < 2; ++b)
; #pragma unroll
;                 for (int m = 0; m < 4; ++m)
; #pragma unroll
;                     for (int n = 0; n < 2; ++n) acc[a][b][m][n] = (f32x4){0.f, 0.f, 0.f, 0.f};
;         cur = nxt; cA = nA; cB = nB; ++ui;
;     }
;     PG8_WAIT_V(0);
;     if (wr == 0) PG8_BAR;
;     PG8_BAR;
	v_mov_b32_dpp v49, v243 quad_perm:[0,1,2,3] row_mask:0xf bank_mask:0x3
	global_store_dwordx4 v252, v[62:65], s[86:87] nt
	global_store_dwordx4 v253, v[46:49], s[86:87] nt
	v_cvt_pk_bf16_f32 v54, v54, v55
	v_cvt_pk_bf16_f32 v55, v56, v57
	v_cvt_pk_bf16_f32 v56, v50, v51
	v_cvt_pk_bf16_f32 v57, v52, v53
	v_cvt_pk_bf16_f32 v30, v30, v31
	v_cvt_pk_bf16_f32 v31, v32, v33
	v_cvt_pk_bf16_f32 v32, v26, v27
	v_cvt_pk_bf16_f32 v33, v28, v29
	v_mov_b32_dpp v240, v54 row_ror:8 row_mask:0xf bank_mask:0xf
	v_mov_b32_dpp v241, v55 row_ror:8 row_mask:0xf bank_mask:0xf
	v_mov_b32_dpp v242, v56 row_ror:8 row_mask:0xf bank_mask:0xf
	v_mov_b32_dpp v243, v57 row_ror:8 row_mask:0xf bank_mask:0xf
	v_mov_b32_dpp v54, v30 row_ror:8 row_mask:0xf bank_mask:0xc
	v_mov_b32_dpp v55, v31 row_ror:8 row_mask:0xf bank_mask:0xc
	v_mov_b32_dpp v56, v32 row_ror:8 row_mask:0xf bank_mask:0xc
	v_mov_b32_dpp v57, v33 row_ror:8 row_mask:0xf bank_mask:0xc
	v_mov_b32_dpp v30, v240 quad_perm:[0,1,2,3] row_mask:0xf bank_mask:0x3
	v_mov_b32_dpp v31, v241 quad_perm:[0,1,2,3] row_mask:0xf bank_mask:0x3
	v_mov_b32_dpp v32, v242 quad_perm:[0,1,2,3] row_mask:0xf bank_mask:0x3
	v_mov_b32_dpp v33, v243 quad_perm:[0,1,2,3] row_mask:0xf bank_mask:0x3
	global_store_dwordx4 v254, v[54:57], s[86:87] nt
	global_store_dwordx4 v255, v[30:33], s[86:87] nt
	v_cvt_pk_bf16_f32 v38, v38, v39
	v_cvt_pk_bf16_f32 v39, v40, v41
	v_cvt_pk_bf16_f32 v40, v34, v35
	v_cvt_pk_bf16_f32 v41, v36, v37
	v_cvt_pk_bf16_f32 v14, v14, v15
	v_cvt_pk_bf16_f32 v15, v16, v17
	v_cvt_pk_bf16_f32 v16, v10, v11
	v_cvt_pk_bf16_f32 v17, v12, v13
	v_mov_b32_dpp v240, v38 row_ror:8 row_mask:0xf bank_mask:0xf
	v_mov_b32_dpp v241, v39 row_ror:8 row_mask:0xf bank_mask:0xf
	v_mov_b32_dpp v242, v40 row_ror:8 row_mask:0xf bank_mask:0xf
	v_mov_b32_dpp v243, v41 row_ror:8 row_mask:0xf bank_mask:0xf
	v_mov_b32_dpp v38, v14 row_ror:8 row_mask:0xf bank_mask:0xc
	v_mov_b32_dpp v39, v15 row_ror:8 row_mask:0xf bank_mask:0xc
	v_mov_b32_dpp v40, v16 row_ror:8 row_mask:0xf bank_mask:0xc
	v_mov_b32_dpp v41, v17 row_ror:8 row_mask:0xf bank_mask:0xc
	v_mov_b32_dpp v14, v240 quad_perm:[0,1,2,3] row_mask:0xf bank_mask:0x3
	v_mov_b32_dpp v15, v241 quad_perm:[0,1,2,3] row_mask:0xf bank_mask:0x3
	v_mov_b32_dpp v16, v242 quad_perm:[0,1,2,3] row_mask:0xf bank_mask:0x3
	v_mov_b32_dpp v17, v243 quad_perm:[0,1,2,3] row_mask:0xf bank_mask:0x3
	global_store_dwordx4 v154, v[38:41], s[86:87] nt
	global_store_dwordx4 v155, v[14:17], s[86:87] nt
	v_cvt_pk_bf16_f32 v22, v22, v23
	v_cvt_pk_bf16_f32 v23, v24, v25
	v_cvt_pk_bf16_f32 v24, v18, v19
	v_cvt_pk_bf16_f32 v25, v20, v21
	v_cvt_pk_bf16_f32 v6, v6, v7
	v_cvt_pk_bf16_f32 v7, v8, v9
	v_cvt_pk_bf16_f32 v8, v2, v3
	v_cvt_pk_bf16_f32 v9, v4, v5
	v_mov_b32_dpp v240, v22 row_ror:8 row_mask:0xf bank_mask:0xf
	v_mov_b32_dpp v241, v23 row_ror:8 row_mask:0xf bank_mask:0xf
	v_mov_b32_dpp v242, v24 row_ror:8 row_mask:0xf bank_mask:0xf
	v_mov_b32_dpp v243, v25 row_ror:8 row_mask:0xf bank_mask:0xf
	v_mov_b32_dpp v22, v6 row_ror:8 row_mask:0xf bank_mask:0xc
	v_mov_b32_dpp v23, v7 row_ror:8 row_mask:0xf bank_mask:0xc
	v_mov_b32_dpp v24, v8 row_ror:8 row_mask:0xf bank_mask:0xc
	v_mov_b32_dpp v25, v9 row_ror:8 row_mask:0xf bank_mask:0xc
	v_mov_b32_dpp v6, v240 quad_perm:[0,1,2,3] row_mask:0xf bank_mask:0x3
	v_mov_b32_dpp v7, v241 quad_perm:[0,1,2,3] row_mask:0xf bank_mask:0x3
	v_mov_b32_dpp v8, v242 quad_perm:[0,1,2,3] row_mask:0xf bank_mask:0x3
	v_mov_b32_dpp v9, v243 quad_perm:[0,1,2,3] row_mask:0xf bank_mask:0x3
	global_store_dwordx4 v156, v[22:25], s[86:87] nt
	global_store_dwordx4 v157, v[6:9], s[86:87] nt
	s_cbranch_vccz .LBB0_1187
	s_waitcnt vmcnt(0)
	s_cmpk_gt_u32 s3, 0xff
	s_cbranch_scc1 .LBB0_1194
	s_barrier
